# v15: v13 + merge-GEMM epilogue rewritten: gate loads of 4 (8 for the last branch) tiles-rows batched under one wait instead of 32 serialized load-wait steps
# speedup vs baseline: 1.0175x; 1.0175x over previous
.LBB0_1421:
	v_mov_b32_e32 v112, v246
	s_lshl_b32 s6, s18, 8
	v_lshrrev_b32_e32 v114, 1, v112
	v_and_or_b32 v112, v112, 15, s54
	v_and_or_b32 v114, v114, 24, s6
	s_lshl_b32 s6, s19, 10
	v_lshl_add_u32 v112, s60, 8, v112
	v_mov_b64_e32 v[144:145], s[30:31]
	s_ashr_i32 s7, s6, 31
	v_mad_i64_i32 v[150:151], s[36:37], v112, s33, v[144:145]
	v_or_b32_e32 v114, s55, v114
	v_lshl_add_u64 v[144:145], s[6:7], 1, v[150:151]
	s_mov_b64 s[36:37], 0x1e00
	v_lshl_add_u64 v[166:167], v[144:145], 0, s[36:37]
	v_ashrrev_i32_e32 v115, 31, v114
	v_lshl_add_u64 v[146:147], v[114:115], 1, v[166:167]
	v_mov_b64_e32 v[214:215], v[146:147]
	v_lshl_add_u64 v[216:217], v[114:115], 1, v[150:151]
	s_mov_b64 s[98:99], 0x1000
	v_lshl_add_u64 v[216:217], v[216:217], 0, s[98:99]
	s_cmp_lt_i32 s19, 2
	s_cselect_b64 s[46:47], -1, 0
	s_cbranch_scc0 .Lmgepi_last
	v_mov_b64_e32 v[210:211], v[214:215]
	global_load_dwordx4 v[144:147], v[210:211], off
	global_load_dwordx4 v[148:151], v[210:211], off offset:256
	global_load_dwordx4 v[152:155], v[210:211], off offset:2048
	global_load_dwordx4 v[156:159], v[210:211], off offset:2304
	s_mov_b64 s[98:99], 0x36000
	v_lshl_add_u64 v[210:211], v[214:215], 0, s[98:99]
	global_load_dwordx4 v[160:163], v[210:211], off
	global_load_dwordx4 v[164:167], v[210:211], off offset:256
	global_load_dwordx4 v[170:173], v[210:211], off offset:2048
	global_load_dwordx4 v[174:177], v[210:211], off offset:2304
	s_waitcnt vmcnt(0)
	v_lshlrev_b32_e32 v178, 16, v144
	v_and_b32_e32 v144, 0xffff0000, v144
	v_lshlrev_b32_e32 v179, 16, v145
	v_and_b32_e32 v145, 0xffff0000, v145
	v_lshlrev_b32_e32 v180, 16, v146
	v_and_b32_e32 v146, 0xffff0000, v146
	v_lshlrev_b32_e32 v181, 16, v147
	v_and_b32_e32 v147, 0xffff0000, v147
	v_mul_f32_e32 v178, 0xbfb8aa3b, v178
	v_mul_f32_e32 v144, 0xbfb8aa3b, v144
	v_mul_f32_e32 v179, 0xbfb8aa3b, v179
	v_mul_f32_e32 v145, 0xbfb8aa3b, v145
	v_mul_f32_e32 v180, 0xbfb8aa3b, v180
	v_mul_f32_e32 v146, 0xbfb8aa3b, v146
	v_mul_f32_e32 v181, 0xbfb8aa3b, v181
	v_mul_f32_e32 v147, 0xbfb8aa3b, v147
	v_exp_f32_e32 v178, v178
	v_exp_f32_e32 v144, v144
	v_exp_f32_e32 v179, v179
	v_exp_f32_e32 v145, v145
	v_exp_f32_e32 v180, v180
	v_exp_f32_e32 v146, v146
	v_exp_f32_e32 v181, v181
	v_exp_f32_e32 v147, v147
	v_lshlrev_b32_e32 v182, 16, v152
	v_and_b32_e32 v152, 0xffff0000, v152
	v_lshlrev_b32_e32 v183, 16, v153
	v_and_b32_e32 v153, 0xffff0000, v153
	v_lshlrev_b32_e32 v184, 16, v154
	v_and_b32_e32 v154, 0xffff0000, v154
	v_lshlrev_b32_e32 v185, 16, v155
	v_and_b32_e32 v155, 0xffff0000, v155
	v_mul_f32_e32 v182, 0xbfb8aa3b, v182
	v_mul_f32_e32 v152, 0xbfb8aa3b, v152
	v_mul_f32_e32 v183, 0xbfb8aa3b, v183
	v_mul_f32_e32 v153, 0xbfb8aa3b, v153
	v_mul_f32_e32 v184, 0xbfb8aa3b, v184
	v_mul_f32_e32 v154, 0xbfb8aa3b, v154
	v_mul_f32_e32 v185, 0xbfb8aa3b, v185
	v_mul_f32_e32 v155, 0xbfb8aa3b, v155
	v_exp_f32_e32 v182, v182
	v_exp_f32_e32 v152, v152
	v_exp_f32_e32 v183, v183
	v_exp_f32_e32 v153, v153
	v_exp_f32_e32 v184, v184
	v_exp_f32_e32 v154, v154
	v_exp_f32_e32 v185, v185
	v_exp_f32_e32 v155, v155
	v_add_f32_e32 v178, 1.0, v178
	v_add_f32_e32 v144, 1.0, v144
	v_add_f32_e32 v179, 1.0, v179
	v_add_f32_e32 v145, 1.0, v145
	v_add_f32_e32 v180, 1.0, v180
	v_add_f32_e32 v146, 1.0, v146
	v_add_f32_e32 v181, 1.0, v181
	v_add_f32_e32 v147, 1.0, v147
	v_add_f32_e32 v182, 1.0, v182
	v_add_f32_e32 v152, 1.0, v152
	v_add_f32_e32 v183, 1.0, v183
	v_add_f32_e32 v153, 1.0, v153
	v_add_f32_e32 v184, 1.0, v184
	v_add_f32_e32 v154, 1.0, v154
	v_add_f32_e32 v185, 1.0, v185
	v_add_f32_e32 v155, 1.0, v155
	v_rcp_f32_e32 v178, v178
	v_rcp_f32_e32 v144, v144
	v_rcp_f32_e32 v179, v179
	v_rcp_f32_e32 v145, v145
	v_rcp_f32_e32 v180, v180
	v_rcp_f32_e32 v146, v146
	v_rcp_f32_e32 v181, v181
	v_rcp_f32_e32 v147, v147
	s_nop 0
	v_mul_f32_e32 v186, v178, v182
	v_mul_f32_e32 v187, v144, v152
	v_mul_f32_e32 v188, v179, v183
	v_mul_f32_e32 v189, v145, v153
	v_mul_f32_e32 v190, v180, v184
	v_mul_f32_e32 v191, v146, v154
	v_mul_f32_e32 v192, v181, v185
	v_mul_f32_e32 v193, v147, v155
	v_pk_mul_f32 v[128:129], v[128:129], v[186:187]
	v_pk_mul_f32 v[130:131], v[130:131], v[188:189]
	v_pk_mul_f32 v[124:125], v[124:125], v[190:191]
	v_pk_mul_f32 v[126:127], v[126:127], v[192:193]
	v_lshlrev_b32_e32 v178, 16, v148
	v_and_b32_e32 v148, 0xffff0000, v148
	v_lshlrev_b32_e32 v179, 16, v149
	v_and_b32_e32 v149, 0xffff0000, v149
	v_lshlrev_b32_e32 v180, 16, v150
	v_and_b32_e32 v150, 0xffff0000, v150
	v_lshlrev_b32_e32 v181, 16, v151
	v_and_b32_e32 v151, 0xffff0000, v151
	v_mul_f32_e32 v178, 0xbfb8aa3b, v178
	v_mul_f32_e32 v148, 0xbfb8aa3b, v148
	v_mul_f32_e32 v179, 0xbfb8aa3b, v179
	v_mul_f32_e32 v149, 0xbfb8aa3b, v149
	v_mul_f32_e32 v180, 0xbfb8aa3b, v180
	v_mul_f32_e32 v150, 0xbfb8aa3b, v150
	v_mul_f32_e32 v181, 0xbfb8aa3b, v181
	v_mul_f32_e32 v151, 0xbfb8aa3b, v151
	v_exp_f32_e32 v178, v178
	v_exp_f32_e32 v148, v148
	v_exp_f32_e32 v179, v179
	v_exp_f32_e32 v149, v149
	v_exp_f32_e32 v180, v180
	v_exp_f32_e32 v150, v150
	v_exp_f32_e32 v181, v181
	v_exp_f32_e32 v151, v151
	v_lshlrev_b32_e32 v182, 16, v156
	v_and_b32_e32 v156, 0xffff0000, v156
	v_lshlrev_b32_e32 v183, 16, v157
	v_and_b32_e32 v157, 0xffff0000, v157
	v_lshlrev_b32_e32 v184, 16, v158
	v_and_b32_e32 v158, 0xffff0000, v158
	v_lshlrev_b32_e32 v185, 16, v159
	v_and_b32_e32 v159, 0xffff0000, v159
	v_mul_f32_e32 v182, 0xbfb8aa3b, v182
	v_mul_f32_e32 v156, 0xbfb8aa3b, v156
	v_mul_f32_e32 v183, 0xbfb8aa3b, v183
	v_mul_f32_e32 v157, 0xbfb8aa3b, v157
	v_mul_f32_e32 v184, 0xbfb8aa3b, v184
	v_mul_f32_e32 v158, 0xbfb8aa3b, v158
	v_mul_f32_e32 v185, 0xbfb8aa3b, v185
	v_mul_f32_e32 v159, 0xbfb8aa3b, v159
	v_exp_f32_e32 v182, v182
	v_exp_f32_e32 v156, v156
	v_exp_f32_e32 v183, v183
	v_exp_f32_e32 v157, v157
	v_exp_f32_e32 v184, v184
	v_exp_f32_e32 v158, v158
	v_exp_f32_e32 v185, v185
	v_exp_f32_e32 v159, v159
	v_add_f32_e32 v178, 1.0, v178
	v_add_f32_e32 v148, 1.0, v148
	v_add_f32_e32 v179, 1.0, v179
	v_add_f32_e32 v149, 1.0, v149
	v_add_f32_e32 v180, 1.0, v180
	v_add_f32_e32 v150, 1.0, v150
	v_add_f32_e32 v181, 1.0, v181
	v_add_f32_e32 v151, 1.0, v151
	v_add_f32_e32 v182, 1.0, v182
	v_add_f32_e32 v156, 1.0, v156
	v_add_f32_e32 v183, 1.0, v183
	v_add_f32_e32 v157, 1.0, v157
	v_add_f32_e32 v184, 1.0, v184
	v_add_f32_e32 v158, 1.0, v158
	v_add_f32_e32 v185, 1.0, v185
	v_add_f32_e32 v159, 1.0, v159
	v_rcp_f32_e32 v178, v178
	v_rcp_f32_e32 v148, v148
	v_rcp_f32_e32 v179, v179
	v_rcp_f32_e32 v149, v149
	v_rcp_f32_e32 v180, v180
	v_rcp_f32_e32 v150, v150
	v_rcp_f32_e32 v181, v181
	v_rcp_f32_e32 v151, v151
	s_nop 0
	v_mul_f32_e32 v186, v178, v182
	v_mul_f32_e32 v187, v148, v156
	v_mul_f32_e32 v188, v179, v183
	v_mul_f32_e32 v189, v149, v157
	v_mul_f32_e32 v190, v180, v184
	v_mul_f32_e32 v191, v150, v158
	v_mul_f32_e32 v192, v181, v185
	v_mul_f32_e32 v193, v151, v159
	v_pk_mul_f32 v[92:93], v[92:93], v[186:187]
	v_pk_mul_f32 v[94:95], v[94:95], v[188:189]
	v_pk_mul_f32 v[88:89], v[88:89], v[190:191]
	v_pk_mul_f32 v[90:91], v[90:91], v[192:193]
	v_lshlrev_b32_e32 v178, 16, v160
	v_and_b32_e32 v160, 0xffff0000, v160
	v_lshlrev_b32_e32 v179, 16, v161
	v_and_b32_e32 v161, 0xffff0000, v161
	v_lshlrev_b32_e32 v180, 16, v162
	v_and_b32_e32 v162, 0xffff0000, v162
	v_lshlrev_b32_e32 v181, 16, v163
	v_and_b32_e32 v163, 0xffff0000, v163
	v_mul_f32_e32 v178, 0xbfb8aa3b, v178
	v_mul_f32_e32 v160, 0xbfb8aa3b, v160
	v_mul_f32_e32 v179, 0xbfb8aa3b, v179
	v_mul_f32_e32 v161, 0xbfb8aa3b, v161
	v_mul_f32_e32 v180, 0xbfb8aa3b, v180
	v_mul_f32_e32 v162, 0xbfb8aa3b, v162
	v_mul_f32_e32 v181, 0xbfb8aa3b, v181
	v_mul_f32_e32 v163, 0xbfb8aa3b, v163
	v_exp_f32_e32 v178, v178
	v_exp_f32_e32 v160, v160
	v_exp_f32_e32 v179, v179
	v_exp_f32_e32 v161, v161
	v_exp_f32_e32 v180, v180
	v_exp_f32_e32 v162, v162
	v_exp_f32_e32 v181, v181
	v_exp_f32_e32 v163, v163
	v_lshlrev_b32_e32 v182, 16, v170
	v_and_b32_e32 v170, 0xffff0000, v170
	v_lshlrev_b32_e32 v183, 16, v171
	v_and_b32_e32 v171, 0xffff0000, v171
	v_lshlrev_b32_e32 v184, 16, v172
	v_and_b32_e32 v172, 0xffff0000, v172
	v_lshlrev_b32_e32 v185, 16, v173
	v_and_b32_e32 v173, 0xffff0000, v173
	v_mul_f32_e32 v182, 0xbfb8aa3b, v182
	v_mul_f32_e32 v170, 0xbfb8aa3b, v170
	v_mul_f32_e32 v183, 0xbfb8aa3b, v183
	v_mul_f32_e32 v171, 0xbfb8aa3b, v171
	v_mul_f32_e32 v184, 0xbfb8aa3b, v184
	v_mul_f32_e32 v172, 0xbfb8aa3b, v172
	v_mul_f32_e32 v185, 0xbfb8aa3b, v185
	v_mul_f32_e32 v173, 0xbfb8aa3b, v173
	v_exp_f32_e32 v182, v182
	v_exp_f32_e32 v170, v170
	v_exp_f32_e32 v183, v183
	v_exp_f32_e32 v171, v171
	v_exp_f32_e32 v184, v184
	v_exp_f32_e32 v172, v172
	v_exp_f32_e32 v185, v185
	v_exp_f32_e32 v173, v173
	v_add_f32_e32 v178, 1.0, v178
	v_add_f32_e32 v160, 1.0, v160
	v_add_f32_e32 v179, 1.0, v179
	v_add_f32_e32 v161, 1.0, v161
	v_add_f32_e32 v180, 1.0, v180
	v_add_f32_e32 v162, 1.0, v162
	v_add_f32_e32 v181, 1.0, v181
	v_add_f32_e32 v163, 1.0, v163
	v_add_f32_e32 v182, 1.0, v182
	v_add_f32_e32 v170, 1.0, v170
	v_add_f32_e32 v183, 1.0, v183
	v_add_f32_e32 v171, 1.0, v171
	v_add_f32_e32 v184, 1.0, v184
	v_add_f32_e32 v172, 1.0, v172
	v_add_f32_e32 v185, 1.0, v185
	v_add_f32_e32 v173, 1.0, v173
	v_rcp_f32_e32 v178, v178
	v_rcp_f32_e32 v160, v160
	v_rcp_f32_e32 v179, v179
	v_rcp_f32_e32 v161, v161
	v_rcp_f32_e32 v180, v180
	v_rcp_f32_e32 v162, v162
	v_rcp_f32_e32 v181, v181
	v_rcp_f32_e32 v163, v163
	s_nop 0
	v_mul_f32_e32 v186, v178, v182
	v_mul_f32_e32 v187, v160, v170
	v_mul_f32_e32 v188, v179, v183
	v_mul_f32_e32 v189, v161, v171
	v_mul_f32_e32 v190, v180, v184
	v_mul_f32_e32 v191, v162, v172
	v_mul_f32_e32 v192, v181, v185
	v_mul_f32_e32 v193, v163, v173
	v_pk_mul_f32 v[120:121], v[120:121], v[186:187]
	v_pk_mul_f32 v[122:123], v[122:123], v[188:189]
	v_pk_mul_f32 v[116:117], v[116:117], v[190:191]
	v_pk_mul_f32 v[118:119], v[118:119], v[192:193]
	v_lshlrev_b32_e32 v178, 16, v164
	v_and_b32_e32 v164, 0xffff0000, v164
	v_lshlrev_b32_e32 v179, 16, v165
	v_and_b32_e32 v165, 0xffff0000, v165
	v_lshlrev_b32_e32 v180, 16, v166
	v_and_b32_e32 v166, 0xffff0000, v166
	v_lshlrev_b32_e32 v181, 16, v167
	v_and_b32_e32 v167, 0xffff0000, v167
	v_mul_f32_e32 v178, 0xbfb8aa3b, v178
	v_mul_f32_e32 v164, 0xbfb8aa3b, v164
	v_mul_f32_e32 v179, 0xbfb8aa3b, v179
	v_mul_f32_e32 v165, 0xbfb8aa3b, v165
	v_mul_f32_e32 v180, 0xbfb8aa3b, v180
	v_mul_f32_e32 v166, 0xbfb8aa3b, v166
	v_mul_f32_e32 v181, 0xbfb8aa3b, v181
	v_mul_f32_e32 v167, 0xbfb8aa3b, v167
	v_exp_f32_e32 v178, v178
	v_exp_f32_e32 v164, v164
	v_exp_f32_e32 v179, v179
	v_exp_f32_e32 v165, v165
	v_exp_f32_e32 v180, v180
	v_exp_f32_e32 v166, v166
	v_exp_f32_e32 v181, v181
	v_exp_f32_e32 v167, v167
	v_lshlrev_b32_e32 v182, 16, v174
	v_and_b32_e32 v174, 0xffff0000, v174
	v_lshlrev_b32_e32 v183, 16, v175
	v_and_b32_e32 v175, 0xffff0000, v175
	v_lshlrev_b32_e32 v184, 16, v176
	v_and_b32_e32 v176, 0xffff0000, v176
	v_lshlrev_b32_e32 v185, 16, v177
	v_and_b32_e32 v177, 0xffff0000, v177
	v_mul_f32_e32 v182, 0xbfb8aa3b, v182
	v_mul_f32_e32 v174, 0xbfb8aa3b, v174
	v_mul_f32_e32 v183, 0xbfb8aa3b, v183
	v_mul_f32_e32 v175, 0xbfb8aa3b, v175
	v_mul_f32_e32 v184, 0xbfb8aa3b, v184
	v_mul_f32_e32 v176, 0xbfb8aa3b, v176
	v_mul_f32_e32 v185, 0xbfb8aa3b, v185
	v_mul_f32_e32 v177, 0xbfb8aa3b, v177
	v_exp_f32_e32 v182, v182
	v_exp_f32_e32 v174, v174
	v_exp_f32_e32 v183, v183
	v_exp_f32_e32 v175, v175
	v_exp_f32_e32 v184, v184
	v_exp_f32_e32 v176, v176
	v_exp_f32_e32 v185, v185
	v_exp_f32_e32 v177, v177
	v_add_f32_e32 v178, 1.0, v178
	v_add_f32_e32 v164, 1.0, v164
	v_add_f32_e32 v179, 1.0, v179
	v_add_f32_e32 v165, 1.0, v165
	v_add_f32_e32 v180, 1.0, v180
	v_add_f32_e32 v166, 1.0, v166
	v_add_f32_e32 v181, 1.0, v181
	v_add_f32_e32 v167, 1.0, v167
	v_add_f32_e32 v182, 1.0, v182
	v_add_f32_e32 v174, 1.0, v174
	v_add_f32_e32 v183, 1.0, v183
	v_add_f32_e32 v175, 1.0, v175
	v_add_f32_e32 v184, 1.0, v184
	v_add_f32_e32 v176, 1.0, v176
	v_add_f32_e32 v185, 1.0, v185
	v_add_f32_e32 v177, 1.0, v177
	v_rcp_f32_e32 v178, v178
	v_rcp_f32_e32 v164, v164
	v_rcp_f32_e32 v179, v179
	v_rcp_f32_e32 v165, v165
	v_rcp_f32_e32 v180, v180
	v_rcp_f32_e32 v166, v166
	v_rcp_f32_e32 v181, v181
	v_rcp_f32_e32 v167, v167
	s_nop 0
	v_mul_f32_e32 v186, v178, v182
	v_mul_f32_e32 v187, v164, v174
	v_mul_f32_e32 v188, v179, v183
	v_mul_f32_e32 v189, v165, v175
	v_mul_f32_e32 v190, v180, v184
	v_mul_f32_e32 v191, v166, v176
	v_mul_f32_e32 v192, v181, v185
	v_mul_f32_e32 v193, v167, v177
	v_pk_mul_f32 v[84:85], v[84:85], v[186:187]
	v_pk_mul_f32 v[86:87], v[86:87], v[188:189]
	v_pk_mul_f32 v[80:81], v[80:81], v[190:191]
	v_pk_mul_f32 v[82:83], v[82:83], v[192:193]
	s_mov_b64 s[98:99], 0x6c000
	v_lshl_add_u64 v[210:211], v[214:215], 0, s[98:99]
	global_load_dwordx4 v[144:147], v[210:211], off
	global_load_dwordx4 v[148:151], v[210:211], off offset:256
	global_load_dwordx4 v[152:155], v[210:211], off offset:2048
	global_load_dwordx4 v[156:159], v[210:211], off offset:2304
	s_mov_b64 s[98:99], 0xa2000
	v_lshl_add_u64 v[210:211], v[214:215], 0, s[98:99]
	global_load_dwordx4 v[160:163], v[210:211], off
	global_load_dwordx4 v[164:167], v[210:211], off offset:256
	global_load_dwordx4 v[170:173], v[210:211], off offset:2048
	global_load_dwordx4 v[174:177], v[210:211], off offset:2304
	s_waitcnt vmcnt(0)
	v_lshlrev_b32_e32 v178, 16, v144
	v_and_b32_e32 v144, 0xffff0000, v144
	v_lshlrev_b32_e32 v179, 16, v145
	v_and_b32_e32 v145, 0xffff0000, v145
	v_lshlrev_b32_e32 v180, 16, v146
	v_and_b32_e32 v146, 0xffff0000, v146
	v_lshlrev_b32_e32 v181, 16, v147
	v_and_b32_e32 v147, 0xffff0000, v147
	v_mul_f32_e32 v178, 0xbfb8aa3b, v178
	v_mul_f32_e32 v144, 0xbfb8aa3b, v144
	v_mul_f32_e32 v179, 0xbfb8aa3b, v179
	v_mul_f32_e32 v145, 0xbfb8aa3b, v145
	v_mul_f32_e32 v180, 0xbfb8aa3b, v180
	v_mul_f32_e32 v146, 0xbfb8aa3b, v146
	v_mul_f32_e32 v181, 0xbfb8aa3b, v181
	v_mul_f32_e32 v147, 0xbfb8aa3b, v147
	v_exp_f32_e32 v178, v178
	v_exp_f32_e32 v144, v144
	v_exp_f32_e32 v179, v179
	v_exp_f32_e32 v145, v145
	v_exp_f32_e32 v180, v180
	v_exp_f32_e32 v146, v146
	v_exp_f32_e32 v181, v181
	v_exp_f32_e32 v147, v147
	v_lshlrev_b32_e32 v182, 16, v152
	v_and_b32_e32 v152, 0xffff0000, v152
	v_lshlrev_b32_e32 v183, 16, v153
	v_and_b32_e32 v153, 0xffff0000, v153
	v_lshlrev_b32_e32 v184, 16, v154
	v_and_b32_e32 v154, 0xffff0000, v154
	v_lshlrev_b32_e32 v185, 16, v155
	v_and_b32_e32 v155, 0xffff0000, v155
	v_mul_f32_e32 v182, 0xbfb8aa3b, v182
	v_mul_f32_e32 v152, 0xbfb8aa3b, v152
	v_mul_f32_e32 v183, 0xbfb8aa3b, v183
	v_mul_f32_e32 v153, 0xbfb8aa3b, v153
	v_mul_f32_e32 v184, 0xbfb8aa3b, v184
	v_mul_f32_e32 v154, 0xbfb8aa3b, v154
	v_mul_f32_e32 v185, 0xbfb8aa3b, v185
	v_mul_f32_e32 v155, 0xbfb8aa3b, v155
	v_exp_f32_e32 v182, v182
	v_exp_f32_e32 v152, v152
	v_exp_f32_e32 v183, v183
	v_exp_f32_e32 v153, v153
	v_exp_f32_e32 v184, v184
	v_exp_f32_e32 v154, v154
	v_exp_f32_e32 v185, v185
	v_exp_f32_e32 v155, v155
	v_add_f32_e32 v178, 1.0, v178
	v_add_f32_e32 v144, 1.0, v144
	v_add_f32_e32 v179, 1.0, v179
	v_add_f32_e32 v145, 1.0, v145
	v_add_f32_e32 v180, 1.0, v180
	v_add_f32_e32 v146, 1.0, v146
	v_add_f32_e32 v181, 1.0, v181
	v_add_f32_e32 v147, 1.0, v147
	v_add_f32_e32 v182, 1.0, v182
	v_add_f32_e32 v152, 1.0, v152
	v_add_f32_e32 v183, 1.0, v183
	v_add_f32_e32 v153, 1.0, v153
	v_add_f32_e32 v184, 1.0, v184
	v_add_f32_e32 v154, 1.0, v154
	v_add_f32_e32 v185, 1.0, v185
	v_add_f32_e32 v155, 1.0, v155
	v_rcp_f32_e32 v178, v178
	v_rcp_f32_e32 v144, v144
	v_rcp_f32_e32 v179, v179
	v_rcp_f32_e32 v145, v145
	v_rcp_f32_e32 v180, v180
	v_rcp_f32_e32 v146, v146
	v_rcp_f32_e32 v181, v181
	v_rcp_f32_e32 v147, v147
	s_nop 0
	v_mul_f32_e32 v186, v178, v182
	v_mul_f32_e32 v187, v144, v152
	v_mul_f32_e32 v188, v179, v183
	v_mul_f32_e32 v189, v145, v153
	v_mul_f32_e32 v190, v180, v184
	v_mul_f32_e32 v191, v146, v154
	v_mul_f32_e32 v192, v181, v185
	v_mul_f32_e32 v193, v147, v155
	v_pk_mul_f32 v[108:109], v[108:109], v[186:187]
	v_pk_mul_f32 v[110:111], v[110:111], v[188:189]
	v_pk_mul_f32 v[104:105], v[104:105], v[190:191]
	v_pk_mul_f32 v[106:107], v[106:107], v[192:193]
	v_lshlrev_b32_e32 v178, 16, v148
	v_and_b32_e32 v148, 0xffff0000, v148
	v_lshlrev_b32_e32 v179, 16, v149
	v_and_b32_e32 v149, 0xffff0000, v149
	v_lshlrev_b32_e32 v180, 16, v150
	v_and_b32_e32 v150, 0xffff0000, v150
	v_lshlrev_b32_e32 v181, 16, v151
	v_and_b32_e32 v151, 0xffff0000, v151
	v_mul_f32_e32 v178, 0xbfb8aa3b, v178
	v_mul_f32_e32 v148, 0xbfb8aa3b, v148
	v_mul_f32_e32 v179, 0xbfb8aa3b, v179
	v_mul_f32_e32 v149, 0xbfb8aa3b, v149
	v_mul_f32_e32 v180, 0xbfb8aa3b, v180
	v_mul_f32_e32 v150, 0xbfb8aa3b, v150
	v_mul_f32_e32 v181, 0xbfb8aa3b, v181
	v_mul_f32_e32 v151, 0xbfb8aa3b, v151
	v_exp_f32_e32 v178, v178
	v_exp_f32_e32 v148, v148
	v_exp_f32_e32 v179, v179
	v_exp_f32_e32 v149, v149
	v_exp_f32_e32 v180, v180
	v_exp_f32_e32 v150, v150
	v_exp_f32_e32 v181, v181
	v_exp_f32_e32 v151, v151
	v_lshlrev_b32_e32 v182, 16, v156
	v_and_b32_e32 v156, 0xffff0000, v156
	v_lshlrev_b32_e32 v183, 16, v157
	v_and_b32_e32 v157, 0xffff0000, v157
	v_lshlrev_b32_e32 v184, 16, v158
	v_and_b32_e32 v158, 0xffff0000, v158
	v_lshlrev_b32_e32 v185, 16, v159
	v_and_b32_e32 v159, 0xffff0000, v159
	v_mul_f32_e32 v182, 0xbfb8aa3b, v182
	v_mul_f32_e32 v156, 0xbfb8aa3b, v156
	v_mul_f32_e32 v183, 0xbfb8aa3b, v183
	v_mul_f32_e32 v157, 0xbfb8aa3b, v157
	v_mul_f32_e32 v184, 0xbfb8aa3b, v184
	v_mul_f32_e32 v158, 0xbfb8aa3b, v158
	v_mul_f32_e32 v185, 0xbfb8aa3b, v185
	v_mul_f32_e32 v159, 0xbfb8aa3b, v159
	v_exp_f32_e32 v182, v182
	v_exp_f32_e32 v156, v156
	v_exp_f32_e32 v183, v183
	v_exp_f32_e32 v157, v157
	v_exp_f32_e32 v184, v184
	v_exp_f32_e32 v158, v158
	v_exp_f32_e32 v185, v185
	v_exp_f32_e32 v159, v159
	v_add_f32_e32 v178, 1.0, v178
	v_add_f32_e32 v148, 1.0, v148
	v_add_f32_e32 v179, 1.0, v179
	v_add_f32_e32 v149, 1.0, v149
	v_add_f32_e32 v180, 1.0, v180
	v_add_f32_e32 v150, 1.0, v150
	v_add_f32_e32 v181, 1.0, v181
	v_add_f32_e32 v151, 1.0, v151
	v_add_f32_e32 v182, 1.0, v182
	v_add_f32_e32 v156, 1.0, v156
	v_add_f32_e32 v183, 1.0, v183
	v_add_f32_e32 v157, 1.0, v157
	v_add_f32_e32 v184, 1.0, v184
	v_add_f32_e32 v158, 1.0, v158
	v_add_f32_e32 v185, 1.0, v185
	v_add_f32_e32 v159, 1.0, v159
	v_rcp_f32_e32 v178, v178
	v_rcp_f32_e32 v148, v148
	v_rcp_f32_e32 v179, v179
	v_rcp_f32_e32 v149, v149
	v_rcp_f32_e32 v180, v180
	v_rcp_f32_e32 v150, v150
	v_rcp_f32_e32 v181, v181
	v_rcp_f32_e32 v151, v151
	s_nop 0
	v_mul_f32_e32 v186, v178, v182
	v_mul_f32_e32 v187, v148, v156
	v_mul_f32_e32 v188, v179, v183
	v_mul_f32_e32 v189, v149, v157
	v_mul_f32_e32 v190, v180, v184
	v_mul_f32_e32 v191, v150, v158
	v_mul_f32_e32 v192, v181, v185
	v_mul_f32_e32 v193, v151, v159
	v_pk_mul_f32 v[76:77], v[76:77], v[186:187]
	v_pk_mul_f32 v[78:79], v[78:79], v[188:189]
	v_pk_mul_f32 v[72:73], v[72:73], v[190:191]
	v_pk_mul_f32 v[74:75], v[74:75], v[192:193]
	v_lshlrev_b32_e32 v178, 16, v160
	v_and_b32_e32 v160, 0xffff0000, v160
	v_lshlrev_b32_e32 v179, 16, v161
	v_and_b32_e32 v161, 0xffff0000, v161
	v_lshlrev_b32_e32 v180, 16, v162
	v_and_b32_e32 v162, 0xffff0000, v162
	v_lshlrev_b32_e32 v181, 16, v163
	v_and_b32_e32 v163, 0xffff0000, v163
	v_mul_f32_e32 v178, 0xbfb8aa3b, v178
	v_mul_f32_e32 v160, 0xbfb8aa3b, v160
	v_mul_f32_e32 v179, 0xbfb8aa3b, v179
	v_mul_f32_e32 v161, 0xbfb8aa3b, v161
	v_mul_f32_e32 v180, 0xbfb8aa3b, v180
	v_mul_f32_e32 v162, 0xbfb8aa3b, v162
	v_mul_f32_e32 v181, 0xbfb8aa3b, v181
	v_mul_f32_e32 v163, 0xbfb8aa3b, v163
	v_exp_f32_e32 v178, v178
	v_exp_f32_e32 v160, v160
	v_exp_f32_e32 v179, v179
	v_exp_f32_e32 v161, v161
	v_exp_f32_e32 v180, v180
	v_exp_f32_e32 v162, v162
	v_exp_f32_e32 v181, v181
	v_exp_f32_e32 v163, v163
	v_lshlrev_b32_e32 v182, 16, v170
	v_and_b32_e32 v170, 0xffff0000, v170
	v_lshlrev_b32_e32 v183, 16, v171
	v_and_b32_e32 v171, 0xffff0000, v171
	v_lshlrev_b32_e32 v184, 16, v172
	v_and_b32_e32 v172, 0xffff0000, v172
	v_lshlrev_b32_e32 v185, 16, v173
	v_and_b32_e32 v173, 0xffff0000, v173
	v_mul_f32_e32 v182, 0xbfb8aa3b, v182
	v_mul_f32_e32 v170, 0xbfb8aa3b, v170
	v_mul_f32_e32 v183, 0xbfb8aa3b, v183
	v_mul_f32_e32 v171, 0xbfb8aa3b, v171
	v_mul_f32_e32 v184, 0xbfb8aa3b, v184
	v_mul_f32_e32 v172, 0xbfb8aa3b, v172
	v_mul_f32_e32 v185, 0xbfb8aa3b, v185
	v_mul_f32_e32 v173, 0xbfb8aa3b, v173
	v_exp_f32_e32 v182, v182
	v_exp_f32_e32 v170, v170
	v_exp_f32_e32 v183, v183
	v_exp_f32_e32 v171, v171
	v_exp_f32_e32 v184, v184
	v_exp_f32_e32 v172, v172
	v_exp_f32_e32 v185, v185
	v_exp_f32_e32 v173, v173
	v_add_f32_e32 v178, 1.0, v178
	v_add_f32_e32 v160, 1.0, v160
	v_add_f32_e32 v179, 1.0, v179
	v_add_f32_e32 v161, 1.0, v161
	v_add_f32_e32 v180, 1.0, v180
	v_add_f32_e32 v162, 1.0, v162
	v_add_f32_e32 v181, 1.0, v181
	v_add_f32_e32 v163, 1.0, v163
	v_add_f32_e32 v182, 1.0, v182
	v_add_f32_e32 v170, 1.0, v170
	v_add_f32_e32 v183, 1.0, v183
	v_add_f32_e32 v171, 1.0, v171
	v_add_f32_e32 v184, 1.0, v184
	v_add_f32_e32 v172, 1.0, v172
	v_add_f32_e32 v185, 1.0, v185
	v_add_f32_e32 v173, 1.0, v173
	v_rcp_f32_e32 v178, v178
	v_rcp_f32_e32 v160, v160
	v_rcp_f32_e32 v179, v179
	v_rcp_f32_e32 v161, v161
	v_rcp_f32_e32 v180, v180
	v_rcp_f32_e32 v162, v162
	v_rcp_f32_e32 v181, v181
	v_rcp_f32_e32 v163, v163
	s_nop 0
	v_mul_f32_e32 v186, v178, v182
	v_mul_f32_e32 v187, v160, v170
	v_mul_f32_e32 v188, v179, v183
	v_mul_f32_e32 v189, v161, v171
	v_mul_f32_e32 v190, v180, v184
	v_mul_f32_e32 v191, v162, v172
	v_mul_f32_e32 v192, v181, v185
	v_mul_f32_e32 v193, v163, v173
	v_pk_mul_f32 v[100:101], v[100:101], v[186:187]
	v_pk_mul_f32 v[102:103], v[102:103], v[188:189]
	v_pk_mul_f32 v[96:97], v[96:97], v[190:191]
	v_pk_mul_f32 v[98:99], v[98:99], v[192:193]
	v_lshlrev_b32_e32 v178, 16, v164
	v_and_b32_e32 v164, 0xffff0000, v164
	v_lshlrev_b32_e32 v179, 16, v165
	v_and_b32_e32 v165, 0xffff0000, v165
	v_lshlrev_b32_e32 v180, 16, v166
	v_and_b32_e32 v166, 0xffff0000, v166
	v_lshlrev_b32_e32 v181, 16, v167
	v_and_b32_e32 v167, 0xffff0000, v167
	v_mul_f32_e32 v178, 0xbfb8aa3b, v178
	v_mul_f32_e32 v164, 0xbfb8aa3b, v164
	v_mul_f32_e32 v179, 0xbfb8aa3b, v179
	v_mul_f32_e32 v165, 0xbfb8aa3b, v165
	v_mul_f32_e32 v180, 0xbfb8aa3b, v180
	v_mul_f32_e32 v166, 0xbfb8aa3b, v166
	v_mul_f32_e32 v181, 0xbfb8aa3b, v181
	v_mul_f32_e32 v167, 0xbfb8aa3b, v167
	v_exp_f32_e32 v178, v178
	v_exp_f32_e32 v164, v164
	v_exp_f32_e32 v179, v179
	v_exp_f32_e32 v165, v165
	v_exp_f32_e32 v180, v180
	v_exp_f32_e32 v166, v166
	v_exp_f32_e32 v181, v181
	v_exp_f32_e32 v167, v167
	v_lshlrev_b32_e32 v182, 16, v174
	v_and_b32_e32 v174, 0xffff0000, v174
	v_lshlrev_b32_e32 v183, 16, v175
	v_and_b32_e32 v175, 0xffff0000, v175
	v_lshlrev_b32_e32 v184, 16, v176
	v_and_b32_e32 v176, 0xffff0000, v176
	v_lshlrev_b32_e32 v185, 16, v177
	v_and_b32_e32 v177, 0xffff0000, v177
	v_mul_f32_e32 v182, 0xbfb8aa3b, v182
	v_mul_f32_e32 v174, 0xbfb8aa3b, v174
	v_mul_f32_e32 v183, 0xbfb8aa3b, v183
	v_mul_f32_e32 v175, 0xbfb8aa3b, v175
	v_mul_f32_e32 v184, 0xbfb8aa3b, v184
	v_mul_f32_e32 v176, 0xbfb8aa3b, v176
	v_mul_f32_e32 v185, 0xbfb8aa3b, v185
	v_mul_f32_e32 v177, 0xbfb8aa3b, v177
	v_exp_f32_e32 v182, v182
	v_exp_f32_e32 v174, v174
	v_exp_f32_e32 v183, v183
	v_exp_f32_e32 v175, v175
	v_exp_f32_e32 v184, v184
	v_exp_f32_e32 v176, v176
	v_exp_f32_e32 v185, v185
	v_exp_f32_e32 v177, v177
	v_add_f32_e32 v178, 1.0, v178
	v_add_f32_e32 v164, 1.0, v164
	v_add_f32_e32 v179, 1.0, v179
	v_add_f32_e32 v165, 1.0, v165
	v_add_f32_e32 v180, 1.0, v180
	v_add_f32_e32 v166, 1.0, v166
	v_add_f32_e32 v181, 1.0, v181
	v_add_f32_e32 v167, 1.0, v167
	v_add_f32_e32 v182, 1.0, v182
	v_add_f32_e32 v174, 1.0, v174
	v_add_f32_e32 v183, 1.0, v183
	v_add_f32_e32 v175, 1.0, v175
	v_add_f32_e32 v184, 1.0, v184
	v_add_f32_e32 v176, 1.0, v176
	v_add_f32_e32 v185, 1.0, v185
	v_add_f32_e32 v177, 1.0, v177
	v_rcp_f32_e32 v178, v178
	v_rcp_f32_e32 v164, v164
	v_rcp_f32_e32 v179, v179
	v_rcp_f32_e32 v165, v165
	v_rcp_f32_e32 v180, v180
	v_rcp_f32_e32 v166, v166
	v_rcp_f32_e32 v181, v181
	v_rcp_f32_e32 v167, v167
	s_nop 0
	v_mul_f32_e32 v186, v178, v182
	v_mul_f32_e32 v187, v164, v174
	v_mul_f32_e32 v188, v179, v183
	v_mul_f32_e32 v189, v165, v175
	v_mul_f32_e32 v190, v180, v184
	v_mul_f32_e32 v191, v166, v176
	v_mul_f32_e32 v192, v181, v185
	v_mul_f32_e32 v193, v167, v177
	v_pk_mul_f32 v[68:69], v[68:69], v[186:187]
	v_pk_mul_f32 v[70:71], v[70:71], v[188:189]
	v_pk_mul_f32 v[64:65], v[64:65], v[190:191]
	v_pk_mul_f32 v[66:67], v[66:67], v[192:193]
	s_mov_b64 s[98:99], 0x1b0000
	v_lshl_add_u64 v[210:211], v[214:215], 0, s[98:99]
	global_load_dwordx4 v[144:147], v[210:211], off
	global_load_dwordx4 v[148:151], v[210:211], off offset:256
	global_load_dwordx4 v[152:155], v[210:211], off offset:2048
	global_load_dwordx4 v[156:159], v[210:211], off offset:2304
	s_mov_b64 s[98:99], 0x1e6000
	v_lshl_add_u64 v[210:211], v[214:215], 0, s[98:99]
	global_load_dwordx4 v[160:163], v[210:211], off
	global_load_dwordx4 v[164:167], v[210:211], off offset:256
	global_load_dwordx4 v[170:173], v[210:211], off offset:2048
	global_load_dwordx4 v[174:177], v[210:211], off offset:2304
	s_waitcnt vmcnt(0)
	v_lshlrev_b32_e32 v178, 16, v144
	v_and_b32_e32 v144, 0xffff0000, v144
	v_lshlrev_b32_e32 v179, 16, v145
	v_and_b32_e32 v145, 0xffff0000, v145
	v_lshlrev_b32_e32 v180, 16, v146
	v_and_b32_e32 v146, 0xffff0000, v146
	v_lshlrev_b32_e32 v181, 16, v147
	v_and_b32_e32 v147, 0xffff0000, v147
	v_mul_f32_e32 v178, 0xbfb8aa3b, v178
	v_mul_f32_e32 v144, 0xbfb8aa3b, v144
	v_mul_f32_e32 v179, 0xbfb8aa3b, v179
	v_mul_f32_e32 v145, 0xbfb8aa3b, v145
	v_mul_f32_e32 v180, 0xbfb8aa3b, v180
	v_mul_f32_e32 v146, 0xbfb8aa3b, v146
	v_mul_f32_e32 v181, 0xbfb8aa3b, v181
	v_mul_f32_e32 v147, 0xbfb8aa3b, v147
	v_exp_f32_e32 v178, v178
	v_exp_f32_e32 v144, v144
	v_exp_f32_e32 v179, v179
	v_exp_f32_e32 v145, v145
	v_exp_f32_e32 v180, v180
	v_exp_f32_e32 v146, v146
	v_exp_f32_e32 v181, v181
	v_exp_f32_e32 v147, v147
	v_lshlrev_b32_e32 v182, 16, v152
	v_and_b32_e32 v152, 0xffff0000, v152
	v_lshlrev_b32_e32 v183, 16, v153
	v_and_b32_e32 v153, 0xffff0000, v153
	v_lshlrev_b32_e32 v184, 16, v154
	v_and_b32_e32 v154, 0xffff0000, v154
	v_lshlrev_b32_e32 v185, 16, v155
	v_and_b32_e32 v155, 0xffff0000, v155
	v_mul_f32_e32 v182, 0xbfb8aa3b, v182
	v_mul_f32_e32 v152, 0xbfb8aa3b, v152
	v_mul_f32_e32 v183, 0xbfb8aa3b, v183
	v_mul_f32_e32 v153, 0xbfb8aa3b, v153
	v_mul_f32_e32 v184, 0xbfb8aa3b, v184
	v_mul_f32_e32 v154, 0xbfb8aa3b, v154
	v_mul_f32_e32 v185, 0xbfb8aa3b, v185
	v_mul_f32_e32 v155, 0xbfb8aa3b, v155
	v_exp_f32_e32 v182, v182
	v_exp_f32_e32 v152, v152
	v_exp_f32_e32 v183, v183
	v_exp_f32_e32 v153, v153
	v_exp_f32_e32 v184, v184
	v_exp_f32_e32 v154, v154
	v_exp_f32_e32 v185, v185
	v_exp_f32_e32 v155, v155
	v_add_f32_e32 v178, 1.0, v178
	v_add_f32_e32 v144, 1.0, v144
	v_add_f32_e32 v179, 1.0, v179
	v_add_f32_e32 v145, 1.0, v145
	v_add_f32_e32 v180, 1.0, v180
	v_add_f32_e32 v146, 1.0, v146
	v_add_f32_e32 v181, 1.0, v181
	v_add_f32_e32 v147, 1.0, v147
	v_add_f32_e32 v182, 1.0, v182
	v_add_f32_e32 v152, 1.0, v152
	v_add_f32_e32 v183, 1.0, v183
	v_add_f32_e32 v153, 1.0, v153
	v_add_f32_e32 v184, 1.0, v184
	v_add_f32_e32 v154, 1.0, v154
	v_add_f32_e32 v185, 1.0, v185
	v_add_f32_e32 v155, 1.0, v155
	v_rcp_f32_e32 v178, v178
	v_rcp_f32_e32 v144, v144
	v_rcp_f32_e32 v179, v179
	v_rcp_f32_e32 v145, v145
	v_rcp_f32_e32 v180, v180
	v_rcp_f32_e32 v146, v146
	v_rcp_f32_e32 v181, v181
	v_rcp_f32_e32 v147, v147
	s_nop 0
	v_mul_f32_e32 v186, v178, v182
	v_mul_f32_e32 v187, v144, v152
	v_mul_f32_e32 v188, v179, v183
	v_mul_f32_e32 v189, v145, v153
	v_mul_f32_e32 v190, v180, v184
	v_mul_f32_e32 v191, v146, v154
	v_mul_f32_e32 v192, v181, v185
	v_mul_f32_e32 v193, v147, v155
	v_pk_mul_f32 v[60:61], v[60:61], v[186:187]
	v_pk_mul_f32 v[62:63], v[62:63], v[188:189]
	v_pk_mul_f32 v[56:57], v[56:57], v[190:191]
	v_pk_mul_f32 v[58:59], v[58:59], v[192:193]
	v_lshlrev_b32_e32 v178, 16, v148
	v_and_b32_e32 v148, 0xffff0000, v148
	v_lshlrev_b32_e32 v179, 16, v149
	v_and_b32_e32 v149, 0xffff0000, v149
	v_lshlrev_b32_e32 v180, 16, v150
	v_and_b32_e32 v150, 0xffff0000, v150
	v_lshlrev_b32_e32 v181, 16, v151
	v_and_b32_e32 v151, 0xffff0000, v151
	v_mul_f32_e32 v178, 0xbfb8aa3b, v178
	v_mul_f32_e32 v148, 0xbfb8aa3b, v148
	v_mul_f32_e32 v179, 0xbfb8aa3b, v179
	v_mul_f32_e32 v149, 0xbfb8aa3b, v149
	v_mul_f32_e32 v180, 0xbfb8aa3b, v180
	v_mul_f32_e32 v150, 0xbfb8aa3b, v150
	v_mul_f32_e32 v181, 0xbfb8aa3b, v181
	v_mul_f32_e32 v151, 0xbfb8aa3b, v151
	v_exp_f32_e32 v178, v178
	v_exp_f32_e32 v148, v148
	v_exp_f32_e32 v179, v179
	v_exp_f32_e32 v149, v149
	v_exp_f32_e32 v180, v180
	v_exp_f32_e32 v150, v150
	v_exp_f32_e32 v181, v181
	v_exp_f32_e32 v151, v151
	v_lshlrev_b32_e32 v182, 16, v156
	v_and_b32_e32 v156, 0xffff0000, v156
	v_lshlrev_b32_e32 v183, 16, v157
	v_and_b32_e32 v157, 0xffff0000, v157
	v_lshlrev_b32_e32 v184, 16, v158
	v_and_b32_e32 v158, 0xffff0000, v158
	v_lshlrev_b32_e32 v185, 16, v159
	v_and_b32_e32 v159, 0xffff0000, v159
	v_mul_f32_e32 v182, 0xbfb8aa3b, v182
	v_mul_f32_e32 v156, 0xbfb8aa3b, v156
	v_mul_f32_e32 v183, 0xbfb8aa3b, v183
	v_mul_f32_e32 v157, 0xbfb8aa3b, v157
	v_mul_f32_e32 v184, 0xbfb8aa3b, v184
	v_mul_f32_e32 v158, 0xbfb8aa3b, v158
	v_mul_f32_e32 v185, 0xbfb8aa3b, v185
	v_mul_f32_e32 v159, 0xbfb8aa3b, v159
	v_exp_f32_e32 v182, v182
	v_exp_f32_e32 v156, v156
	v_exp_f32_e32 v183, v183
	v_exp_f32_e32 v157, v157
	v_exp_f32_e32 v184, v184
	v_exp_f32_e32 v158, v158
	v_exp_f32_e32 v185, v185
	v_exp_f32_e32 v159, v159
	v_add_f32_e32 v178, 1.0, v178
	v_add_f32_e32 v148, 1.0, v148
	v_add_f32_e32 v179, 1.0, v179
	v_add_f32_e32 v149, 1.0, v149
	v_add_f32_e32 v180, 1.0, v180
	v_add_f32_e32 v150, 1.0, v150
	v_add_f32_e32 v181, 1.0, v181
	v_add_f32_e32 v151, 1.0, v151
	v_add_f32_e32 v182, 1.0, v182
	v_add_f32_e32 v156, 1.0, v156
	v_add_f32_e32 v183, 1.0, v183
	v_add_f32_e32 v157, 1.0, v157
	v_add_f32_e32 v184, 1.0, v184
	v_add_f32_e32 v158, 1.0, v158
	v_add_f32_e32 v185, 1.0, v185
	v_add_f32_e32 v159, 1.0, v159
	v_rcp_f32_e32 v178, v178
	v_rcp_f32_e32 v148, v148
	v_rcp_f32_e32 v179, v179
	v_rcp_f32_e32 v149, v149
	v_rcp_f32_e32 v180, v180
	v_rcp_f32_e32 v150, v150
	v_rcp_f32_e32 v181, v181
	v_rcp_f32_e32 v151, v151
	s_nop 0
	v_mul_f32_e32 v186, v178, v182
	v_mul_f32_e32 v187, v148, v156
	v_mul_f32_e32 v188, v179, v183
	v_mul_f32_e32 v189, v149, v157
	v_mul_f32_e32 v190, v180, v184
	v_mul_f32_e32 v191, v150, v158
	v_mul_f32_e32 v192, v181, v185
	v_mul_f32_e32 v193, v151, v159
	v_pk_mul_f32 v[28:29], v[28:29], v[186:187]
	v_pk_mul_f32 v[30:31], v[30:31], v[188:189]
	v_pk_mul_f32 v[24:25], v[24:25], v[190:191]
	v_pk_mul_f32 v[26:27], v[26:27], v[192:193]
	v_lshlrev_b32_e32 v178, 16, v160
	v_and_b32_e32 v160, 0xffff0000, v160
	v_lshlrev_b32_e32 v179, 16, v161
	v_and_b32_e32 v161, 0xffff0000, v161
	v_lshlrev_b32_e32 v180, 16, v162
	v_and_b32_e32 v162, 0xffff0000, v162
	v_lshlrev_b32_e32 v181, 16, v163
	v_and_b32_e32 v163, 0xffff0000, v163
	v_mul_f32_e32 v178, 0xbfb8aa3b, v178
	v_mul_f32_e32 v160, 0xbfb8aa3b, v160
	v_mul_f32_e32 v179, 0xbfb8aa3b, v179
	v_mul_f32_e32 v161, 0xbfb8aa3b, v161
	v_mul_f32_e32 v180, 0xbfb8aa3b, v180
	v_mul_f32_e32 v162, 0xbfb8aa3b, v162
	v_mul_f32_e32 v181, 0xbfb8aa3b, v181
	v_mul_f32_e32 v163, 0xbfb8aa3b, v163
	v_exp_f32_e32 v178, v178
	v_exp_f32_e32 v160, v160
	v_exp_f32_e32 v179, v179
	v_exp_f32_e32 v161, v161
	v_exp_f32_e32 v180, v180
	v_exp_f32_e32 v162, v162
	v_exp_f32_e32 v181, v181
	v_exp_f32_e32 v163, v163
	v_lshlrev_b32_e32 v182, 16, v170
	v_and_b32_e32 v170, 0xffff0000, v170
	v_lshlrev_b32_e32 v183, 16, v171
	v_and_b32_e32 v171, 0xffff0000, v171
	v_lshlrev_b32_e32 v184, 16, v172
	v_and_b32_e32 v172, 0xffff0000, v172
	v_lshlrev_b32_e32 v185, 16, v173
	v_and_b32_e32 v173, 0xffff0000, v173
	v_mul_f32_e32 v182, 0xbfb8aa3b, v182
	v_mul_f32_e32 v170, 0xbfb8aa3b, v170
	v_mul_f32_e32 v183, 0xbfb8aa3b, v183
	v_mul_f32_e32 v171, 0xbfb8aa3b, v171
	v_mul_f32_e32 v184, 0xbfb8aa3b, v184
	v_mul_f32_e32 v172, 0xbfb8aa3b, v172
	v_mul_f32_e32 v185, 0xbfb8aa3b, v185
	v_mul_f32_e32 v173, 0xbfb8aa3b, v173
	v_exp_f32_e32 v182, v182
	v_exp_f32_e32 v170, v170
	v_exp_f32_e32 v183, v183
	v_exp_f32_e32 v171, v171
	v_exp_f32_e32 v184, v184
	v_exp_f32_e32 v172, v172
	v_exp_f32_e32 v185, v185
	v_exp_f32_e32 v173, v173
	v_add_f32_e32 v178, 1.0, v178
	v_add_f32_e32 v160, 1.0, v160
	v_add_f32_e32 v179, 1.0, v179
	v_add_f32_e32 v161, 1.0, v161
	v_add_f32_e32 v180, 1.0, v180
	v_add_f32_e32 v162, 1.0, v162
	v_add_f32_e32 v181, 1.0, v181
	v_add_f32_e32 v163, 1.0, v163
	v_add_f32_e32 v182, 1.0, v182
	v_add_f32_e32 v170, 1.0, v170
	v_add_f32_e32 v183, 1.0, v183
	v_add_f32_e32 v171, 1.0, v171
	v_add_f32_e32 v184, 1.0, v184
	v_add_f32_e32 v172, 1.0, v172
	v_add_f32_e32 v185, 1.0, v185
	v_add_f32_e32 v173, 1.0, v173
	v_rcp_f32_e32 v178, v178
	v_rcp_f32_e32 v160, v160
	v_rcp_f32_e32 v179, v179
	v_rcp_f32_e32 v161, v161
	v_rcp_f32_e32 v180, v180
	v_rcp_f32_e32 v162, v162
	v_rcp_f32_e32 v181, v181
	v_rcp_f32_e32 v163, v163
	s_nop 0
	v_mul_f32_e32 v186, v178, v182
	v_mul_f32_e32 v187, v160, v170
	v_mul_f32_e32 v188, v179, v183
	v_mul_f32_e32 v189, v161, v171
	v_mul_f32_e32 v190, v180, v184
	v_mul_f32_e32 v191, v162, v172
	v_mul_f32_e32 v192, v181, v185
	v_mul_f32_e32 v193, v163, v173
	v_pk_mul_f32 v[52:53], v[52:53], v[186:187]
	v_pk_mul_f32 v[54:55], v[54:55], v[188:189]
	v_pk_mul_f32 v[48:49], v[48:49], v[190:191]
	v_pk_mul_f32 v[50:51], v[50:51], v[192:193]
	v_lshlrev_b32_e32 v178, 16, v164
	v_and_b32_e32 v164, 0xffff0000, v164
	v_lshlrev_b32_e32 v179, 16, v165
	v_and_b32_e32 v165, 0xffff0000, v165
	v_lshlrev_b32_e32 v180, 16, v166
	v_and_b32_e32 v166, 0xffff0000, v166
	v_lshlrev_b32_e32 v181, 16, v167
	v_and_b32_e32 v167, 0xffff0000, v167
	v_mul_f32_e32 v178, 0xbfb8aa3b, v178
	v_mul_f32_e32 v164, 0xbfb8aa3b, v164
	v_mul_f32_e32 v179, 0xbfb8aa3b, v179
	v_mul_f32_e32 v165, 0xbfb8aa3b, v165
	v_mul_f32_e32 v180, 0xbfb8aa3b, v180
	v_mul_f32_e32 v166, 0xbfb8aa3b, v166
	v_mul_f32_e32 v181, 0xbfb8aa3b, v181
	v_mul_f32_e32 v167, 0xbfb8aa3b, v167
	v_exp_f32_e32 v178, v178
	v_exp_f32_e32 v164, v164
	v_exp_f32_e32 v179, v179
	v_exp_f32_e32 v165, v165
	v_exp_f32_e32 v180, v180
	v_exp_f32_e32 v166, v166
	v_exp_f32_e32 v181, v181
	v_exp_f32_e32 v167, v167
	v_lshlrev_b32_e32 v182, 16, v174
	v_and_b32_e32 v174, 0xffff0000, v174
	v_lshlrev_b32_e32 v183, 16, v175
	v_and_b32_e32 v175, 0xffff0000, v175
	v_lshlrev_b32_e32 v184, 16, v176
	v_and_b32_e32 v176, 0xffff0000, v176
	v_lshlrev_b32_e32 v185, 16, v177
	v_and_b32_e32 v177, 0xffff0000, v177
	v_mul_f32_e32 v182, 0xbfb8aa3b, v182
	v_mul_f32_e32 v174, 0xbfb8aa3b, v174
	v_mul_f32_e32 v183, 0xbfb8aa3b, v183
	v_mul_f32_e32 v175, 0xbfb8aa3b, v175
	v_mul_f32_e32 v184, 0xbfb8aa3b, v184
	v_mul_f32_e32 v176, 0xbfb8aa3b, v176
	v_mul_f32_e32 v185, 0xbfb8aa3b, v185
	v_mul_f32_e32 v177, 0xbfb8aa3b, v177
	v_exp_f32_e32 v182, v182
	v_exp_f32_e32 v174, v174
	v_exp_f32_e32 v183, v183
	v_exp_f32_e32 v175, v175
	v_exp_f32_e32 v184, v184
	v_exp_f32_e32 v176, v176
	v_exp_f32_e32 v185, v185
	v_exp_f32_e32 v177, v177
	v_add_f32_e32 v178, 1.0, v178
	v_add_f32_e32 v164, 1.0, v164
	v_add_f32_e32 v179, 1.0, v179
	v_add_f32_e32 v165, 1.0, v165
	v_add_f32_e32 v180, 1.0, v180
	v_add_f32_e32 v166, 1.0, v166
	v_add_f32_e32 v181, 1.0, v181
	v_add_f32_e32 v167, 1.0, v167
	v_add_f32_e32 v182, 1.0, v182
	v_add_f32_e32 v174, 1.0, v174
	v_add_f32_e32 v183, 1.0, v183
	v_add_f32_e32 v175, 1.0, v175
	v_add_f32_e32 v184, 1.0, v184
	v_add_f32_e32 v176, 1.0, v176
	v_add_f32_e32 v185, 1.0, v185
	v_add_f32_e32 v177, 1.0, v177
	v_rcp_f32_e32 v178, v178
	v_rcp_f32_e32 v164, v164
	v_rcp_f32_e32 v179, v179
	v_rcp_f32_e32 v165, v165
	v_rcp_f32_e32 v180, v180
	v_rcp_f32_e32 v166, v166
	v_rcp_f32_e32 v181, v181
	v_rcp_f32_e32 v167, v167
	s_nop 0
	v_mul_f32_e32 v186, v178, v182
	v_mul_f32_e32 v187, v164, v174
	v_mul_f32_e32 v188, v179, v183
	v_mul_f32_e32 v189, v165, v175
	v_mul_f32_e32 v190, v180, v184
	v_mul_f32_e32 v191, v166, v176
	v_mul_f32_e32 v192, v181, v185
	v_mul_f32_e32 v193, v167, v177
	v_pk_mul_f32 v[20:21], v[20:21], v[186:187]
	v_pk_mul_f32 v[22:23], v[22:23], v[188:189]
	v_pk_mul_f32 v[16:17], v[16:17], v[190:191]
	v_pk_mul_f32 v[18:19], v[18:19], v[192:193]
	s_mov_b64 s[98:99], 0x21c000
	v_lshl_add_u64 v[210:211], v[214:215], 0, s[98:99]
	global_load_dwordx4 v[144:147], v[210:211], off
	global_load_dwordx4 v[148:151], v[210:211], off offset:256
	global_load_dwordx4 v[152:155], v[210:211], off offset:2048
	global_load_dwordx4 v[156:159], v[210:211], off offset:2304
	s_mov_b64 s[98:99], 0x252000
	v_lshl_add_u64 v[210:211], v[214:215], 0, s[98:99]
	global_load_dwordx4 v[160:163], v[210:211], off
	global_load_dwordx4 v[164:167], v[210:211], off offset:256
	global_load_dwordx4 v[170:173], v[210:211], off offset:2048
	global_load_dwordx4 v[174:177], v[210:211], off offset:2304
	s_waitcnt vmcnt(0)
	v_lshlrev_b32_e32 v178, 16, v144
	v_and_b32_e32 v144, 0xffff0000, v144
	v_lshlrev_b32_e32 v179, 16, v145
	v_and_b32_e32 v145, 0xffff0000, v145
	v_lshlrev_b32_e32 v180, 16, v146
	v_and_b32_e32 v146, 0xffff0000, v146
	v_lshlrev_b32_e32 v181, 16, v147
	v_and_b32_e32 v147, 0xffff0000, v147
	v_mul_f32_e32 v178, 0xbfb8aa3b, v178
	v_mul_f32_e32 v144, 0xbfb8aa3b, v144
	v_mul_f32_e32 v179, 0xbfb8aa3b, v179
	v_mul_f32_e32 v145, 0xbfb8aa3b, v145
	v_mul_f32_e32 v180, 0xbfb8aa3b, v180
	v_mul_f32_e32 v146, 0xbfb8aa3b, v146
	v_mul_f32_e32 v181, 0xbfb8aa3b, v181
	v_mul_f32_e32 v147, 0xbfb8aa3b, v147
	v_exp_f32_e32 v178, v178
	v_exp_f32_e32 v144, v144
	v_exp_f32_e32 v179, v179
	v_exp_f32_e32 v145, v145
	v_exp_f32_e32 v180, v180
	v_exp_f32_e32 v146, v146
	v_exp_f32_e32 v181, v181
	v_exp_f32_e32 v147, v147
	v_lshlrev_b32_e32 v182, 16, v152
	v_and_b32_e32 v152, 0xffff0000, v152
	v_lshlrev_b32_e32 v183, 16, v153
	v_and_b32_e32 v153, 0xffff0000, v153
	v_lshlrev_b32_e32 v184, 16, v154
	v_and_b32_e32 v154, 0xffff0000, v154
	v_lshlrev_b32_e32 v185, 16, v155
	v_and_b32_e32 v155, 0xffff0000, v155
	v_mul_f32_e32 v182, 0xbfb8aa3b, v182
	v_mul_f32_e32 v152, 0xbfb8aa3b, v152
	v_mul_f32_e32 v183, 0xbfb8aa3b, v183
	v_mul_f32_e32 v153, 0xbfb8aa3b, v153
	v_mul_f32_e32 v184, 0xbfb8aa3b, v184
	v_mul_f32_e32 v154, 0xbfb8aa3b, v154
	v_mul_f32_e32 v185, 0xbfb8aa3b, v185
	v_mul_f32_e32 v155, 0xbfb8aa3b, v155
	v_exp_f32_e32 v182, v182
	v_exp_f32_e32 v152, v152
	v_exp_f32_e32 v183, v183
	v_exp_f32_e32 v153, v153
	v_exp_f32_e32 v184, v184
	v_exp_f32_e32 v154, v154
	v_exp_f32_e32 v185, v185
	v_exp_f32_e32 v155, v155
	v_add_f32_e32 v178, 1.0, v178
	v_add_f32_e32 v144, 1.0, v144
	v_add_f32_e32 v179, 1.0, v179
	v_add_f32_e32 v145, 1.0, v145
	v_add_f32_e32 v180, 1.0, v180
	v_add_f32_e32 v146, 1.0, v146
	v_add_f32_e32 v181, 1.0, v181
	v_add_f32_e32 v147, 1.0, v147
	v_add_f32_e32 v182, 1.0, v182
	v_add_f32_e32 v152, 1.0, v152
	v_add_f32_e32 v183, 1.0, v183
	v_add_f32_e32 v153, 1.0, v153
	v_add_f32_e32 v184, 1.0, v184
	v_add_f32_e32 v154, 1.0, v154
	v_add_f32_e32 v185, 1.0, v185
	v_add_f32_e32 v155, 1.0, v155
	v_rcp_f32_e32 v178, v178
	v_rcp_f32_e32 v144, v144
	v_rcp_f32_e32 v179, v179
	v_rcp_f32_e32 v145, v145
	v_rcp_f32_e32 v180, v180
	v_rcp_f32_e32 v146, v146
	v_rcp_f32_e32 v181, v181
	v_rcp_f32_e32 v147, v147
	s_nop 0
	v_mul_f32_e32 v186, v178, v182
	v_mul_f32_e32 v187, v144, v152
	v_mul_f32_e32 v188, v179, v183
	v_mul_f32_e32 v189, v145, v153
	v_mul_f32_e32 v190, v180, v184
	v_mul_f32_e32 v191, v146, v154
	v_mul_f32_e32 v192, v181, v185
	v_mul_f32_e32 v193, v147, v155
	v_pk_mul_f32 v[44:45], v[44:45], v[186:187]
	v_pk_mul_f32 v[46:47], v[46:47], v[188:189]
	v_pk_mul_f32 v[40:41], v[40:41], v[190:191]
	v_pk_mul_f32 v[42:43], v[42:43], v[192:193]
	v_lshlrev_b32_e32 v178, 16, v148
	v_and_b32_e32 v148, 0xffff0000, v148
	v_lshlrev_b32_e32 v179, 16, v149
	v_and_b32_e32 v149, 0xffff0000, v149
	v_lshlrev_b32_e32 v180, 16, v150
	v_and_b32_e32 v150, 0xffff0000, v150
	v_lshlrev_b32_e32 v181, 16, v151
	v_and_b32_e32 v151, 0xffff0000, v151
	v_mul_f32_e32 v178, 0xbfb8aa3b, v178
	v_mul_f32_e32 v148, 0xbfb8aa3b, v148
	v_mul_f32_e32 v179, 0xbfb8aa3b, v179
	v_mul_f32_e32 v149, 0xbfb8aa3b, v149
	v_mul_f32_e32 v180, 0xbfb8aa3b, v180
	v_mul_f32_e32 v150, 0xbfb8aa3b, v150
	v_mul_f32_e32 v181, 0xbfb8aa3b, v181
	v_mul_f32_e32 v151, 0xbfb8aa3b, v151
	v_exp_f32_e32 v178, v178
	v_exp_f32_e32 v148, v148
	v_exp_f32_e32 v179, v179
	v_exp_f32_e32 v149, v149
	v_exp_f32_e32 v180, v180
	v_exp_f32_e32 v150, v150
	v_exp_f32_e32 v181, v181
	v_exp_f32_e32 v151, v151
	v_lshlrev_b32_e32 v182, 16, v156
	v_and_b32_e32 v156, 0xffff0000, v156
	v_lshlrev_b32_e32 v183, 16, v157
	v_and_b32_e32 v157, 0xffff0000, v157
	v_lshlrev_b32_e32 v184, 16, v158
	v_and_b32_e32 v158, 0xffff0000, v158
	v_lshlrev_b32_e32 v185, 16, v159
	v_and_b32_e32 v159, 0xffff0000, v159
	v_mul_f32_e32 v182, 0xbfb8aa3b, v182
	v_mul_f32_e32 v156, 0xbfb8aa3b, v156
	v_mul_f32_e32 v183, 0xbfb8aa3b, v183
	v_mul_f32_e32 v157, 0xbfb8aa3b, v157
	v_mul_f32_e32 v184, 0xbfb8aa3b, v184
	v_mul_f32_e32 v158, 0xbfb8aa3b, v158
	v_mul_f32_e32 v185, 0xbfb8aa3b, v185
	v_mul_f32_e32 v159, 0xbfb8aa3b, v159
	v_exp_f32_e32 v182, v182
	v_exp_f32_e32 v156, v156
	v_exp_f32_e32 v183, v183
	v_exp_f32_e32 v157, v157
	v_exp_f32_e32 v184, v184
	v_exp_f32_e32 v158, v158
	v_exp_f32_e32 v185, v185
	v_exp_f32_e32 v159, v159
	v_add_f32_e32 v178, 1.0, v178
	v_add_f32_e32 v148, 1.0, v148
	v_add_f32_e32 v179, 1.0, v179
	v_add_f32_e32 v149, 1.0, v149
	v_add_f32_e32 v180, 1.0, v180
	v_add_f32_e32 v150, 1.0, v150
	v_add_f32_e32 v181, 1.0, v181
	v_add_f32_e32 v151, 1.0, v151
	v_add_f32_e32 v182, 1.0, v182
	v_add_f32_e32 v156, 1.0, v156
	v_add_f32_e32 v183, 1.0, v183
	v_add_f32_e32 v157, 1.0, v157
	v_add_f32_e32 v184, 1.0, v184
	v_add_f32_e32 v158, 1.0, v158
	v_add_f32_e32 v185, 1.0, v185
	v_add_f32_e32 v159, 1.0, v159
	v_rcp_f32_e32 v178, v178
	v_rcp_f32_e32 v148, v148
	v_rcp_f32_e32 v179, v179
	v_rcp_f32_e32 v149, v149
	v_rcp_f32_e32 v180, v180
	v_rcp_f32_e32 v150, v150
	v_rcp_f32_e32 v181, v181
	v_rcp_f32_e32 v151, v151
	s_nop 0
	v_mul_f32_e32 v186, v178, v182
	v_mul_f32_e32 v187, v148, v156
	v_mul_f32_e32 v188, v179, v183
	v_mul_f32_e32 v189, v149, v157
	v_mul_f32_e32 v190, v180, v184
	v_mul_f32_e32 v191, v150, v158
	v_mul_f32_e32 v192, v181, v185
	v_mul_f32_e32 v193, v151, v159
	v_pk_mul_f32 v[12:13], v[12:13], v[186:187]
	v_pk_mul_f32 v[14:15], v[14:15], v[188:189]
	v_pk_mul_f32 v[8:9], v[8:9], v[190:191]
	v_pk_mul_f32 v[10:11], v[10:11], v[192:193]
	v_lshlrev_b32_e32 v178, 16, v160
	v_and_b32_e32 v160, 0xffff0000, v160
	v_lshlrev_b32_e32 v179, 16, v161
	v_and_b32_e32 v161, 0xffff0000, v161
	v_lshlrev_b32_e32 v180, 16, v162
	v_and_b32_e32 v162, 0xffff0000, v162
	v_lshlrev_b32_e32 v181, 16, v163
	v_and_b32_e32 v163, 0xffff0000, v163
	v_mul_f32_e32 v178, 0xbfb8aa3b, v178
	v_mul_f32_e32 v160, 0xbfb8aa3b, v160
	v_mul_f32_e32 v179, 0xbfb8aa3b, v179
	v_mul_f32_e32 v161, 0xbfb8aa3b, v161
	v_mul_f32_e32 v180, 0xbfb8aa3b, v180
	v_mul_f32_e32 v162, 0xbfb8aa3b, v162
	v_mul_f32_e32 v181, 0xbfb8aa3b, v181
	v_mul_f32_e32 v163, 0xbfb8aa3b, v163
	v_exp_f32_e32 v178, v178
	v_exp_f32_e32 v160, v160
	v_exp_f32_e32 v179, v179
	v_exp_f32_e32 v161, v161
	v_exp_f32_e32 v180, v180
	v_exp_f32_e32 v162, v162
	v_exp_f32_e32 v181, v181
	v_exp_f32_e32 v163, v163
	v_lshlrev_b32_e32 v182, 16, v170
	v_and_b32_e32 v170, 0xffff0000, v170
	v_lshlrev_b32_e32 v183, 16, v171
	v_and_b32_e32 v171, 0xffff0000, v171
	v_lshlrev_b32_e32 v184, 16, v172
	v_and_b32_e32 v172, 0xffff0000, v172
	v_lshlrev_b32_e32 v185, 16, v173
	v_and_b32_e32 v173, 0xffff0000, v173
	v_mul_f32_e32 v182, 0xbfb8aa3b, v182
	v_mul_f32_e32 v170, 0xbfb8aa3b, v170
	v_mul_f32_e32 v183, 0xbfb8aa3b, v183
	v_mul_f32_e32 v171, 0xbfb8aa3b, v171
	v_mul_f32_e32 v184, 0xbfb8aa3b, v184
	v_mul_f32_e32 v172, 0xbfb8aa3b, v172
	v_mul_f32_e32 v185, 0xbfb8aa3b, v185
	v_mul_f32_e32 v173, 0xbfb8aa3b, v173
	v_exp_f32_e32 v182, v182
	v_exp_f32_e32 v170, v170
	v_exp_f32_e32 v183, v183
	v_exp_f32_e32 v171, v171
	v_exp_f32_e32 v184, v184
	v_exp_f32_e32 v172, v172
	v_exp_f32_e32 v185, v185
	v_exp_f32_e32 v173, v173
	v_add_f32_e32 v178, 1.0, v178
	v_add_f32_e32 v160, 1.0, v160
	v_add_f32_e32 v179, 1.0, v179
	v_add_f32_e32 v161, 1.0, v161
	v_add_f32_e32 v180, 1.0, v180
	v_add_f32_e32 v162, 1.0, v162
	v_add_f32_e32 v181, 1.0, v181
	v_add_f32_e32 v163, 1.0, v163
	v_add_f32_e32 v182, 1.0, v182
	v_add_f32_e32 v170, 1.0, v170
	v_add_f32_e32 v183, 1.0, v183
	v_add_f32_e32 v171, 1.0, v171
	v_add_f32_e32 v184, 1.0, v184
	v_add_f32_e32 v172, 1.0, v172
	v_add_f32_e32 v185, 1.0, v185
	v_add_f32_e32 v173, 1.0, v173
	v_rcp_f32_e32 v178, v178
	v_rcp_f32_e32 v160, v160
	v_rcp_f32_e32 v179, v179
	v_rcp_f32_e32 v161, v161
	v_rcp_f32_e32 v180, v180
	v_rcp_f32_e32 v162, v162
	v_rcp_f32_e32 v181, v181
	v_rcp_f32_e32 v163, v163
	s_nop 0
	v_mul_f32_e32 v186, v178, v182
	v_mul_f32_e32 v187, v160, v170
	v_mul_f32_e32 v188, v179, v183
	v_mul_f32_e32 v189, v161, v171
	v_mul_f32_e32 v190, v180, v184
	v_mul_f32_e32 v191, v162, v172
	v_mul_f32_e32 v192, v181, v185
	v_mul_f32_e32 v193, v163, v173
	v_pk_mul_f32 v[36:37], v[36:37], v[186:187]
	v_pk_mul_f32 v[38:39], v[38:39], v[188:189]
	v_pk_mul_f32 v[32:33], v[32:33], v[190:191]
	v_pk_mul_f32 v[34:35], v[34:35], v[192:193]
	v_lshlrev_b32_e32 v178, 16, v164
	v_and_b32_e32 v164, 0xffff0000, v164
	v_lshlrev_b32_e32 v179, 16, v165
	v_and_b32_e32 v165, 0xffff0000, v165
	v_lshlrev_b32_e32 v180, 16, v166
	v_and_b32_e32 v166, 0xffff0000, v166
	v_lshlrev_b32_e32 v181, 16, v167
	v_and_b32_e32 v167, 0xffff0000, v167
	v_mul_f32_e32 v178, 0xbfb8aa3b, v178
	v_mul_f32_e32 v164, 0xbfb8aa3b, v164
	v_mul_f32_e32 v179, 0xbfb8aa3b, v179
	v_mul_f32_e32 v165, 0xbfb8aa3b, v165
	v_mul_f32_e32 v180, 0xbfb8aa3b, v180
	v_mul_f32_e32 v166, 0xbfb8aa3b, v166
	v_mul_f32_e32 v181, 0xbfb8aa3b, v181
	v_mul_f32_e32 v167, 0xbfb8aa3b, v167
	v_exp_f32_e32 v178, v178
	v_exp_f32_e32 v164, v164
	v_exp_f32_e32 v179, v179
	v_exp_f32_e32 v165, v165
	v_exp_f32_e32 v180, v180
	v_exp_f32_e32 v166, v166
	v_exp_f32_e32 v181, v181
	v_exp_f32_e32 v167, v167
	v_lshlrev_b32_e32 v182, 16, v174
	v_and_b32_e32 v174, 0xffff0000, v174
	v_lshlrev_b32_e32 v183, 16, v175
	v_and_b32_e32 v175, 0xffff0000, v175
	v_lshlrev_b32_e32 v184, 16, v176
	v_and_b32_e32 v176, 0xffff0000, v176
	v_lshlrev_b32_e32 v185, 16, v177
	v_and_b32_e32 v177, 0xffff0000, v177
	v_mul_f32_e32 v182, 0xbfb8aa3b, v182
	v_mul_f32_e32 v174, 0xbfb8aa3b, v174
	v_mul_f32_e32 v183, 0xbfb8aa3b, v183
	v_mul_f32_e32 v175, 0xbfb8aa3b, v175
	v_mul_f32_e32 v184, 0xbfb8aa3b, v184
	v_mul_f32_e32 v176, 0xbfb8aa3b, v176
	v_mul_f32_e32 v185, 0xbfb8aa3b, v185
	v_mul_f32_e32 v177, 0xbfb8aa3b, v177
	v_exp_f32_e32 v182, v182
	v_exp_f32_e32 v174, v174
	v_exp_f32_e32 v183, v183
	v_exp_f32_e32 v175, v175
	v_exp_f32_e32 v184, v184
	v_exp_f32_e32 v176, v176
	v_exp_f32_e32 v185, v185
	v_exp_f32_e32 v177, v177
	v_add_f32_e32 v178, 1.0, v178
	v_add_f32_e32 v164, 1.0, v164
	v_add_f32_e32 v179, 1.0, v179
	v_add_f32_e32 v165, 1.0, v165
	v_add_f32_e32 v180, 1.0, v180
	v_add_f32_e32 v166, 1.0, v166
	v_add_f32_e32 v181, 1.0, v181
	v_add_f32_e32 v167, 1.0, v167
	v_add_f32_e32 v182, 1.0, v182
	v_add_f32_e32 v174, 1.0, v174
	v_add_f32_e32 v183, 1.0, v183
	v_add_f32_e32 v175, 1.0, v175
	v_add_f32_e32 v184, 1.0, v184
	v_add_f32_e32 v176, 1.0, v176
	v_add_f32_e32 v185, 1.0, v185
	v_add_f32_e32 v177, 1.0, v177
	v_rcp_f32_e32 v178, v178
	v_rcp_f32_e32 v164, v164
	v_rcp_f32_e32 v179, v179
	v_rcp_f32_e32 v165, v165
	v_rcp_f32_e32 v180, v180
	v_rcp_f32_e32 v166, v166
	v_rcp_f32_e32 v181, v181
	v_rcp_f32_e32 v167, v167
	s_nop 0
	v_mul_f32_e32 v186, v178, v182
	v_mul_f32_e32 v187, v164, v174
	v_mul_f32_e32 v188, v179, v183
	v_mul_f32_e32 v189, v165, v175
	v_mul_f32_e32 v190, v180, v184
	v_mul_f32_e32 v191, v166, v176
	v_mul_f32_e32 v192, v181, v185
	v_mul_f32_e32 v193, v167, v177
	v_pk_mul_f32 v[4:5], v[4:5], v[186:187]
	v_pk_mul_f32 v[6:7], v[6:7], v[188:189]
	v_pk_mul_f32 v[0:1], v[0:1], v[190:191]
	v_pk_mul_f32 v[2:3], v[2:3], v[192:193]
	s_branch .Lmgepi_done
.Lmgepi_last:
	v_mov_b64_e32 v[210:211], v[214:215]
	global_load_dwordx4 v[144:147], v[210:211], off
	global_load_dwordx4 v[148:151], v[210:211], off offset:256
	s_mov_b64 s[98:99], 0x36000
	v_lshl_add_u64 v[210:211], v[214:215], 0, s[98:99]
	global_load_dwordx4 v[152:155], v[210:211], off
	global_load_dwordx4 v[156:159], v[210:211], off offset:256
	s_mov_b64 s[98:99], 0x6c000
	v_lshl_add_u64 v[210:211], v[214:215], 0, s[98:99]
	global_load_dwordx4 v[160:163], v[210:211], off
	global_load_dwordx4 v[164:167], v[210:211], off offset:256
	s_mov_b64 s[98:99], 0xa2000
	v_lshl_add_u64 v[210:211], v[214:215], 0, s[98:99]
	global_load_dwordx4 v[170:173], v[210:211], off
	global_load_dwordx4 v[174:177], v[210:211], off offset:256
	s_waitcnt vmcnt(0)
	v_mov_b64_e32 v[210:211], v[216:217]
	v_lshlrev_b32_e32 v178, 16, v144
	v_and_b32_e32 v144, 0xffff0000, v144
	v_lshlrev_b32_e32 v179, 16, v145
	v_and_b32_e32 v145, 0xffff0000, v145
	v_lshlrev_b32_e32 v180, 16, v146
	v_and_b32_e32 v146, 0xffff0000, v146
	v_lshlrev_b32_e32 v181, 16, v147
	v_and_b32_e32 v147, 0xffff0000, v147
	v_mul_f32_e32 v178, 0xbfb8aa3b, v178
	v_mul_f32_e32 v144, 0xbfb8aa3b, v144
	v_mul_f32_e32 v179, 0xbfb8aa3b, v179
	v_mul_f32_e32 v145, 0xbfb8aa3b, v145
	v_mul_f32_e32 v180, 0xbfb8aa3b, v180
	v_mul_f32_e32 v146, 0xbfb8aa3b, v146
	v_mul_f32_e32 v181, 0xbfb8aa3b, v181
	v_mul_f32_e32 v147, 0xbfb8aa3b, v147
	v_exp_f32_e32 v178, v178
	v_exp_f32_e32 v144, v144
	v_exp_f32_e32 v179, v179
	v_exp_f32_e32 v145, v145
	v_exp_f32_e32 v180, v180
	v_exp_f32_e32 v146, v146
	v_exp_f32_e32 v181, v181
	v_exp_f32_e32 v147, v147
	v_add_f32_e32 v178, 1.0, v178
	v_add_f32_e32 v144, 1.0, v144
	v_add_f32_e32 v179, 1.0, v179
	v_add_f32_e32 v145, 1.0, v145
	v_add_f32_e32 v180, 1.0, v180
	v_add_f32_e32 v146, 1.0, v146
	v_add_f32_e32 v181, 1.0, v181
	v_add_f32_e32 v147, 1.0, v147
	v_rcp_f32_e32 v178, v178
	v_rcp_f32_e32 v144, v144
	v_rcp_f32_e32 v179, v179
	v_rcp_f32_e32 v145, v145
	v_rcp_f32_e32 v180, v180
	v_rcp_f32_e32 v146, v146
	v_rcp_f32_e32 v181, v181
	v_rcp_f32_e32 v147, v147
	s_nop 0
	v_mul_f32_e32 v186, v128, v178
	v_mul_f32_e32 v187, v129, v144
	v_mul_f32_e32 v188, v130, v179
	v_mul_f32_e32 v189, v131, v145
	v_mul_f32_e32 v190, v124, v180
	v_mul_f32_e32 v191, v125, v146
	v_mul_f32_e32 v192, v126, v181
	v_mul_f32_e32 v193, v127, v147
	v_cvt_pk_bf16_f32 v144, v186, v187
	v_cvt_pk_bf16_f32 v145, v188, v189
	v_cvt_pk_bf16_f32 v146, v190, v191
	v_cvt_pk_bf16_f32 v147, v192, v193
	global_store_dwordx4 v[210:211], v[144:147], off
	v_lshlrev_b32_e32 v178, 16, v148
	v_and_b32_e32 v148, 0xffff0000, v148
	v_lshlrev_b32_e32 v179, 16, v149
	v_and_b32_e32 v149, 0xffff0000, v149
	v_lshlrev_b32_e32 v180, 16, v150
	v_and_b32_e32 v150, 0xffff0000, v150
	v_lshlrev_b32_e32 v181, 16, v151
	v_and_b32_e32 v151, 0xffff0000, v151
	v_mul_f32_e32 v178, 0xbfb8aa3b, v178
	v_mul_f32_e32 v148, 0xbfb8aa3b, v148
	v_mul_f32_e32 v179, 0xbfb8aa3b, v179
	v_mul_f32_e32 v149, 0xbfb8aa3b, v149
	v_mul_f32_e32 v180, 0xbfb8aa3b, v180
	v_mul_f32_e32 v150, 0xbfb8aa3b, v150
	v_mul_f32_e32 v181, 0xbfb8aa3b, v181
	v_mul_f32_e32 v151, 0xbfb8aa3b, v151
	v_exp_f32_e32 v178, v178
	v_exp_f32_e32 v148, v148
	v_exp_f32_e32 v179, v179
	v_exp_f32_e32 v149, v149
	v_exp_f32_e32 v180, v180
	v_exp_f32_e32 v150, v150
	v_exp_f32_e32 v181, v181
	v_exp_f32_e32 v151, v151
	v_add_f32_e32 v178, 1.0, v178
	v_add_f32_e32 v148, 1.0, v148
	v_add_f32_e32 v179, 1.0, v179
	v_add_f32_e32 v149, 1.0, v149
	v_add_f32_e32 v180, 1.0, v180
	v_add_f32_e32 v150, 1.0, v150
	v_add_f32_e32 v181, 1.0, v181
	v_add_f32_e32 v151, 1.0, v151
	v_rcp_f32_e32 v178, v178
	v_rcp_f32_e32 v148, v148
	v_rcp_f32_e32 v179, v179
	v_rcp_f32_e32 v149, v149
	v_rcp_f32_e32 v180, v180
	v_rcp_f32_e32 v150, v150
	v_rcp_f32_e32 v181, v181
	v_rcp_f32_e32 v151, v151
	s_nop 0
	v_mul_f32_e32 v186, v92, v178
	v_mul_f32_e32 v187, v93, v148
	v_mul_f32_e32 v188, v94, v179
	v_mul_f32_e32 v189, v95, v149
	v_mul_f32_e32 v190, v88, v180
	v_mul_f32_e32 v191, v89, v150
	v_mul_f32_e32 v192, v90, v181
	v_mul_f32_e32 v193, v91, v151
	v_cvt_pk_bf16_f32 v148, v186, v187
	v_cvt_pk_bf16_f32 v149, v188, v189
	v_cvt_pk_bf16_f32 v150, v190, v191
	v_cvt_pk_bf16_f32 v151, v192, v193
	global_store_dwordx4 v[210:211], v[148:151], off offset:256
	s_mov_b64 s[98:99], 0x36000
	v_lshl_add_u64 v[210:211], v[216:217], 0, s[98:99]
	v_lshlrev_b32_e32 v178, 16, v152
	v_and_b32_e32 v152, 0xffff0000, v152
	v_lshlrev_b32_e32 v179, 16, v153
	v_and_b32_e32 v153, 0xffff0000, v153
	v_lshlrev_b32_e32 v180, 16, v154
	v_and_b32_e32 v154, 0xffff0000, v154
	v_lshlrev_b32_e32 v181, 16, v155
	v_and_b32_e32 v155, 0xffff0000, v155
	v_mul_f32_e32 v178, 0xbfb8aa3b, v178
	v_mul_f32_e32 v152, 0xbfb8aa3b, v152
	v_mul_f32_e32 v179, 0xbfb8aa3b, v179
	v_mul_f32_e32 v153, 0xbfb8aa3b, v153
	v_mul_f32_e32 v180, 0xbfb8aa3b, v180
	v_mul_f32_e32 v154, 0xbfb8aa3b, v154
	v_mul_f32_e32 v181, 0xbfb8aa3b, v181
	v_mul_f32_e32 v155, 0xbfb8aa3b, v155
	v_exp_f32_e32 v178, v178
	v_exp_f32_e32 v152, v152
	v_exp_f32_e32 v179, v179
	v_exp_f32_e32 v153, v153
	v_exp_f32_e32 v180, v180
	v_exp_f32_e32 v154, v154
	v_exp_f32_e32 v181, v181
	v_exp_f32_e32 v155, v155
	v_add_f32_e32 v178, 1.0, v178
	v_add_f32_e32 v152, 1.0, v152
	v_add_f32_e32 v179, 1.0, v179
	v_add_f32_e32 v153, 1.0, v153
	v_add_f32_e32 v180, 1.0, v180
	v_add_f32_e32 v154, 1.0, v154
	v_add_f32_e32 v181, 1.0, v181
	v_add_f32_e32 v155, 1.0, v155
	v_rcp_f32_e32 v178, v178
	v_rcp_f32_e32 v152, v152
	v_rcp_f32_e32 v179, v179
	v_rcp_f32_e32 v153, v153
	v_rcp_f32_e32 v180, v180
	v_rcp_f32_e32 v154, v154
	v_rcp_f32_e32 v181, v181
	v_rcp_f32_e32 v155, v155
	s_nop 0
	v_mul_f32_e32 v186, v120, v178
	v_mul_f32_e32 v187, v121, v152
	v_mul_f32_e32 v188, v122, v179
	v_mul_f32_e32 v189, v123, v153
	v_mul_f32_e32 v190, v116, v180
	v_mul_f32_e32 v191, v117, v154
	v_mul_f32_e32 v192, v118, v181
	v_mul_f32_e32 v193, v119, v155
	v_cvt_pk_bf16_f32 v152, v186, v187
	v_cvt_pk_bf16_f32 v153, v188, v189
	v_cvt_pk_bf16_f32 v154, v190, v191
	v_cvt_pk_bf16_f32 v155, v192, v193
	global_store_dwordx4 v[210:211], v[152:155], off
	v_lshlrev_b32_e32 v178, 16, v156
	v_and_b32_e32 v156, 0xffff0000, v156
	v_lshlrev_b32_e32 v179, 16, v157
	v_and_b32_e32 v157, 0xffff0000, v157
	v_lshlrev_b32_e32 v180, 16, v158
	v_and_b32_e32 v158, 0xffff0000, v158
	v_lshlrev_b32_e32 v181, 16, v159
	v_and_b32_e32 v159, 0xffff0000, v159
	v_mul_f32_e32 v178, 0xbfb8aa3b, v178
	v_mul_f32_e32 v156, 0xbfb8aa3b, v156
	v_mul_f32_e32 v179, 0xbfb8aa3b, v179
	v_mul_f32_e32 v157, 0xbfb8aa3b, v157
	v_mul_f32_e32 v180, 0xbfb8aa3b, v180
	v_mul_f32_e32 v158, 0xbfb8aa3b, v158
	v_mul_f32_e32 v181, 0xbfb8aa3b, v181
	v_mul_f32_e32 v159, 0xbfb8aa3b, v159
	v_exp_f32_e32 v178, v178
	v_exp_f32_e32 v156, v156
	v_exp_f32_e32 v179, v179
	v_exp_f32_e32 v157, v157
	v_exp_f32_e32 v180, v180
	v_exp_f32_e32 v158, v158
	v_exp_f32_e32 v181, v181
	v_exp_f32_e32 v159, v159
	v_add_f32_e32 v178, 1.0, v178
	v_add_f32_e32 v156, 1.0, v156
	v_add_f32_e32 v179, 1.0, v179
	v_add_f32_e32 v157, 1.0, v157
	v_add_f32_e32 v180, 1.0, v180
	v_add_f32_e32 v158, 1.0, v158
	v_add_f32_e32 v181, 1.0, v181
	v_add_f32_e32 v159, 1.0, v159
	v_rcp_f32_e32 v178, v178
	v_rcp_f32_e32 v156, v156
	v_rcp_f32_e32 v179, v179
	v_rcp_f32_e32 v157, v157
	v_rcp_f32_e32 v180, v180
	v_rcp_f32_e32 v158, v158
	v_rcp_f32_e32 v181, v181
	v_rcp_f32_e32 v159, v159
	s_nop 0
	v_mul_f32_e32 v186, v84, v178
	v_mul_f32_e32 v187, v85, v156
	v_mul_f32_e32 v188, v86, v179
	v_mul_f32_e32 v189, v87, v157
	v_mul_f32_e32 v190, v80, v180
	v_mul_f32_e32 v191, v81, v158
	v_mul_f32_e32 v192, v82, v181
	v_mul_f32_e32 v193, v83, v159
	v_cvt_pk_bf16_f32 v156, v186, v187
	v_cvt_pk_bf16_f32 v157, v188, v189
	v_cvt_pk_bf16_f32 v158, v190, v191
	v_cvt_pk_bf16_f32 v159, v192, v193
	global_store_dwordx4 v[210:211], v[156:159], off offset:256
	s_mov_b64 s[98:99], 0x6c000
	v_lshl_add_u64 v[210:211], v[216:217], 0, s[98:99]
	v_lshlrev_b32_e32 v178, 16, v160
	v_and_b32_e32 v160, 0xffff0000, v160
	v_lshlrev_b32_e32 v179, 16, v161
	v_and_b32_e32 v161, 0xffff0000, v161
	v_lshlrev_b32_e32 v180, 16, v162
	v_and_b32_e32 v162, 0xffff0000, v162
	v_lshlrev_b32_e32 v181, 16, v163
	v_and_b32_e32 v163, 0xffff0000, v163
	v_mul_f32_e32 v178, 0xbfb8aa3b, v178
	v_mul_f32_e32 v160, 0xbfb8aa3b, v160
	v_mul_f32_e32 v179, 0xbfb8aa3b, v179
	v_mul_f32_e32 v161, 0xbfb8aa3b, v161
	v_mul_f32_e32 v180, 0xbfb8aa3b, v180
	v_mul_f32_e32 v162, 0xbfb8aa3b, v162
	v_mul_f32_e32 v181, 0xbfb8aa3b, v181
	v_mul_f32_e32 v163, 0xbfb8aa3b, v163
	v_exp_f32_e32 v178, v178
	v_exp_f32_e32 v160, v160
	v_exp_f32_e32 v179, v179
	v_exp_f32_e32 v161, v161
	v_exp_f32_e32 v180, v180
	v_exp_f32_e32 v162, v162
	v_exp_f32_e32 v181, v181
	v_exp_f32_e32 v163, v163
	v_add_f32_e32 v178, 1.0, v178
	v_add_f32_e32 v160, 1.0, v160
	v_add_f32_e32 v179, 1.0, v179
	v_add_f32_e32 v161, 1.0, v161
	v_add_f32_e32 v180, 1.0, v180
	v_add_f32_e32 v162, 1.0, v162
	v_add_f32_e32 v181, 1.0, v181
	v_add_f32_e32 v163, 1.0, v163
	v_rcp_f32_e32 v178, v178
	v_rcp_f32_e32 v160, v160
	v_rcp_f32_e32 v179, v179
	v_rcp_f32_e32 v161, v161
	v_rcp_f32_e32 v180, v180
	v_rcp_f32_e32 v162, v162
	v_rcp_f32_e32 v181, v181
	v_rcp_f32_e32 v163, v163
	s_nop 0
	v_mul_f32_e32 v186, v108, v178
	v_mul_f32_e32 v187, v109, v160
	v_mul_f32_e32 v188, v110, v179
	v_mul_f32_e32 v189, v111, v161
	v_mul_f32_e32 v190, v104, v180
	v_mul_f32_e32 v191, v105, v162
	v_mul_f32_e32 v192, v106, v181
	v_mul_f32_e32 v193, v107, v163
	v_cvt_pk_bf16_f32 v160, v186, v187
	v_cvt_pk_bf16_f32 v161, v188, v189
	v_cvt_pk_bf16_f32 v162, v190, v191
	v_cvt_pk_bf16_f32 v163, v192, v193
	global_store_dwordx4 v[210:211], v[160:163], off
	v_lshlrev_b32_e32 v178, 16, v164
	v_and_b32_e32 v164, 0xffff0000, v164
	v_lshlrev_b32_e32 v179, 16, v165
	v_and_b32_e32 v165, 0xffff0000, v165
	v_lshlrev_b32_e32 v180, 16, v166
	v_and_b32_e32 v166, 0xffff0000, v166
	v_lshlrev_b32_e32 v181, 16, v167
	v_and_b32_e32 v167, 0xffff0000, v167
	v_mul_f32_e32 v178, 0xbfb8aa3b, v178
	v_mul_f32_e32 v164, 0xbfb8aa3b, v164
	v_mul_f32_e32 v179, 0xbfb8aa3b, v179
	v_mul_f32_e32 v165, 0xbfb8aa3b, v165
	v_mul_f32_e32 v180, 0xbfb8aa3b, v180
	v_mul_f32_e32 v166, 0xbfb8aa3b, v166
	v_mul_f32_e32 v181, 0xbfb8aa3b, v181
	v_mul_f32_e32 v167, 0xbfb8aa3b, v167
	v_exp_f32_e32 v178, v178
	v_exp_f32_e32 v164, v164
	v_exp_f32_e32 v179, v179
	v_exp_f32_e32 v165, v165
	v_exp_f32_e32 v180, v180
	v_exp_f32_e32 v166, v166
	v_exp_f32_e32 v181, v181
	v_exp_f32_e32 v167, v167
	v_add_f32_e32 v178, 1.0, v178
	v_add_f32_e32 v164, 1.0, v164
	v_add_f32_e32 v179, 1.0, v179
	v_add_f32_e32 v165, 1.0, v165
	v_add_f32_e32 v180, 1.0, v180
	v_add_f32_e32 v166, 1.0, v166
	v_add_f32_e32 v181, 1.0, v181
	v_add_f32_e32 v167, 1.0, v167
	v_rcp_f32_e32 v178, v178
	v_rcp_f32_e32 v164, v164
	v_rcp_f32_e32 v179, v179
	v_rcp_f32_e32 v165, v165
	v_rcp_f32_e32 v180, v180
	v_rcp_f32_e32 v166, v166
	v_rcp_f32_e32 v181, v181
	v_rcp_f32_e32 v167, v167
	s_nop 0
	v_mul_f32_e32 v186, v76, v178
	v_mul_f32_e32 v187, v77, v164
	v_mul_f32_e32 v188, v78, v179
	v_mul_f32_e32 v189, v79, v165
	v_mul_f32_e32 v190, v72, v180
	v_mul_f32_e32 v191, v73, v166
	v_mul_f32_e32 v192, v74, v181
	v_mul_f32_e32 v193, v75, v167
	v_cvt_pk_bf16_f32 v164, v186, v187
	v_cvt_pk_bf16_f32 v165, v188, v189
	v_cvt_pk_bf16_f32 v166, v190, v191
	v_cvt_pk_bf16_f32 v167, v192, v193
	global_store_dwordx4 v[210:211], v[164:167], off offset:256
	s_mov_b64 s[98:99], 0xa2000
	v_lshl_add_u64 v[210:211], v[216:217], 0, s[98:99]
	v_lshlrev_b32_e32 v178, 16, v170
	v_and_b32_e32 v170, 0xffff0000, v170
	v_lshlrev_b32_e32 v179, 16, v171
	v_and_b32_e32 v171, 0xffff0000, v171
	v_lshlrev_b32_e32 v180, 16, v172
	v_and_b32_e32 v172, 0xffff0000, v172
	v_lshlrev_b32_e32 v181, 16, v173
	v_and_b32_e32 v173, 0xffff0000, v173
	v_mul_f32_e32 v178, 0xbfb8aa3b, v178
	v_mul_f32_e32 v170, 0xbfb8aa3b, v170
	v_mul_f32_e32 v179, 0xbfb8aa3b, v179
	v_mul_f32_e32 v171, 0xbfb8aa3b, v171
	v_mul_f32_e32 v180, 0xbfb8aa3b, v180
	v_mul_f32_e32 v172, 0xbfb8aa3b, v172
	v_mul_f32_e32 v181, 0xbfb8aa3b, v181
	v_mul_f32_e32 v173, 0xbfb8aa3b, v173
	v_exp_f32_e32 v178, v178
	v_exp_f32_e32 v170, v170
	v_exp_f32_e32 v179, v179
	v_exp_f32_e32 v171, v171
	v_exp_f32_e32 v180, v180
	v_exp_f32_e32 v172, v172
	v_exp_f32_e32 v181, v181
	v_exp_f32_e32 v173, v173
	v_add_f32_e32 v178, 1.0, v178
	v_add_f32_e32 v170, 1.0, v170
	v_add_f32_e32 v179, 1.0, v179
	v_add_f32_e32 v171, 1.0, v171
	v_add_f32_e32 v180, 1.0, v180
	v_add_f32_e32 v172, 1.0, v172
	v_add_f32_e32 v181, 1.0, v181
	v_add_f32_e32 v173, 1.0, v173
	v_rcp_f32_e32 v178, v178
	v_rcp_f32_e32 v170, v170
	v_rcp_f32_e32 v179, v179
	v_rcp_f32_e32 v171, v171
	v_rcp_f32_e32 v180, v180
	v_rcp_f32_e32 v172, v172
	v_rcp_f32_e32 v181, v181
	v_rcp_f32_e32 v173, v173
	s_nop 0
	v_mul_f32_e32 v186, v100, v178
	v_mul_f32_e32 v187, v101, v170
	v_mul_f32_e32 v188, v102, v179
	v_mul_f32_e32 v189, v103, v171
	v_mul_f32_e32 v190, v96, v180
	v_mul_f32_e32 v191, v97, v172
	v_mul_f32_e32 v192, v98, v181
	v_mul_f32_e32 v193, v99, v173
	v_cvt_pk_bf16_f32 v170, v186, v187
	v_cvt_pk_bf16_f32 v171, v188, v189
	v_cvt_pk_bf16_f32 v172, v190, v191
	v_cvt_pk_bf16_f32 v173, v192, v193
	global_store_dwordx4 v[210:211], v[170:173], off
	v_lshlrev_b32_e32 v178, 16, v174
	v_and_b32_e32 v174, 0xffff0000, v174
	v_lshlrev_b32_e32 v179, 16, v175
	v_and_b32_e32 v175, 0xffff0000, v175
	v_lshlrev_b32_e32 v180, 16, v176
	v_and_b32_e32 v176, 0xffff0000, v176
	v_lshlrev_b32_e32 v181, 16, v177
	v_and_b32_e32 v177, 0xffff0000, v177
	v_mul_f32_e32 v178, 0xbfb8aa3b, v178
	v_mul_f32_e32 v174, 0xbfb8aa3b, v174
	v_mul_f32_e32 v179, 0xbfb8aa3b, v179
	v_mul_f32_e32 v175, 0xbfb8aa3b, v175
	v_mul_f32_e32 v180, 0xbfb8aa3b, v180
	v_mul_f32_e32 v176, 0xbfb8aa3b, v176
	v_mul_f32_e32 v181, 0xbfb8aa3b, v181
	v_mul_f32_e32 v177, 0xbfb8aa3b, v177
	v_exp_f32_e32 v178, v178
	v_exp_f32_e32 v174, v174
	v_exp_f32_e32 v179, v179
	v_exp_f32_e32 v175, v175
	v_exp_f32_e32 v180, v180
	v_exp_f32_e32 v176, v176
	v_exp_f32_e32 v181, v181
	v_exp_f32_e32 v177, v177
	v_add_f32_e32 v178, 1.0, v178
	v_add_f32_e32 v174, 1.0, v174
	v_add_f32_e32 v179, 1.0, v179
	v_add_f32_e32 v175, 1.0, v175
	v_add_f32_e32 v180, 1.0, v180
	v_add_f32_e32 v176, 1.0, v176
	v_add_f32_e32 v181, 1.0, v181
	v_add_f32_e32 v177, 1.0, v177
	v_rcp_f32_e32 v178, v178
	v_rcp_f32_e32 v174, v174
	v_rcp_f32_e32 v179, v179
	v_rcp_f32_e32 v175, v175
	v_rcp_f32_e32 v180, v180
	v_rcp_f32_e32 v176, v176
	v_rcp_f32_e32 v181, v181
	v_rcp_f32_e32 v177, v177
	s_nop 0
	v_mul_f32_e32 v186, v68, v178
	v_mul_f32_e32 v187, v69, v174
	v_mul_f32_e32 v188, v70, v179
	v_mul_f32_e32 v189, v71, v175
	v_mul_f32_e32 v190, v64, v180
	v_mul_f32_e32 v191, v65, v176
	v_mul_f32_e32 v192, v66, v181
	v_mul_f32_e32 v193, v67, v177
	v_cvt_pk_bf16_f32 v174, v186, v187
	v_cvt_pk_bf16_f32 v175, v188, v189
	v_cvt_pk_bf16_f32 v176, v190, v191
	v_cvt_pk_bf16_f32 v177, v192, v193
	global_store_dwordx4 v[210:211], v[174:177], off offset:256
	s_mov_b64 s[98:99], 0x1b0000
	v_lshl_add_u64 v[210:211], v[214:215], 0, s[98:99]
	global_load_dwordx4 v[144:147], v[210:211], off
	global_load_dwordx4 v[148:151], v[210:211], off offset:256
	s_mov_b64 s[98:99], 0x1e6000
	v_lshl_add_u64 v[210:211], v[214:215], 0, s[98:99]
	global_load_dwordx4 v[152:155], v[210:211], off
	global_load_dwordx4 v[156:159], v[210:211], off offset:256
	s_mov_b64 s[98:99], 0x21c000
	v_lshl_add_u64 v[210:211], v[214:215], 0, s[98:99]
	global_load_dwordx4 v[160:163], v[210:211], off
	global_load_dwordx4 v[164:167], v[210:211], off offset:256
	s_mov_b64 s[98:99], 0x252000
	v_lshl_add_u64 v[210:211], v[214:215], 0, s[98:99]
	global_load_dwordx4 v[170:173], v[210:211], off
	global_load_dwordx4 v[174:177], v[210:211], off offset:256
	s_waitcnt vmcnt(0)
	s_mov_b64 s[98:99], 0x1b0000
	v_lshl_add_u64 v[210:211], v[216:217], 0, s[98:99]
	v_lshlrev_b32_e32 v178, 16, v144
	v_and_b32_e32 v144, 0xffff0000, v144
	v_lshlrev_b32_e32 v179, 16, v145
	v_and_b32_e32 v145, 0xffff0000, v145
	v_lshlrev_b32_e32 v180, 16, v146
	v_and_b32_e32 v146, 0xffff0000, v146
	v_lshlrev_b32_e32 v181, 16, v147
	v_and_b32_e32 v147, 0xffff0000, v147
	v_mul_f32_e32 v178, 0xbfb8aa3b, v178
	v_mul_f32_e32 v144, 0xbfb8aa3b, v144
	v_mul_f32_e32 v179, 0xbfb8aa3b, v179
	v_mul_f32_e32 v145, 0xbfb8aa3b, v145
	v_mul_f32_e32 v180, 0xbfb8aa3b, v180
	v_mul_f32_e32 v146, 0xbfb8aa3b, v146
	v_mul_f32_e32 v181, 0xbfb8aa3b, v181
	v_mul_f32_e32 v147, 0xbfb8aa3b, v147
	v_exp_f32_e32 v178, v178
	v_exp_f32_e32 v144, v144
	v_exp_f32_e32 v179, v179
	v_exp_f32_e32 v145, v145
	v_exp_f32_e32 v180, v180
	v_exp_f32_e32 v146, v146
	v_exp_f32_e32 v181, v181
	v_exp_f32_e32 v147, v147
	v_add_f32_e32 v178, 1.0, v178
	v_add_f32_e32 v144, 1.0, v144
	v_add_f32_e32 v179, 1.0, v179
	v_add_f32_e32 v145, 1.0, v145
	v_add_f32_e32 v180, 1.0, v180
	v_add_f32_e32 v146, 1.0, v146
	v_add_f32_e32 v181, 1.0, v181
	v_add_f32_e32 v147, 1.0, v147
	v_rcp_f32_e32 v178, v178
	v_rcp_f32_e32 v144, v144
	v_rcp_f32_e32 v179, v179
	v_rcp_f32_e32 v145, v145
	v_rcp_f32_e32 v180, v180
	v_rcp_f32_e32 v146, v146
	v_rcp_f32_e32 v181, v181
	v_rcp_f32_e32 v147, v147
	s_nop 0
	v_mul_f32_e32 v186, v60, v178
	v_mul_f32_e32 v187, v61, v144
	v_mul_f32_e32 v188, v62, v179
	v_mul_f32_e32 v189, v63, v145
	v_mul_f32_e32 v190, v56, v180
	v_mul_f32_e32 v191, v57, v146
	v_mul_f32_e32 v192, v58, v181
	v_mul_f32_e32 v193, v59, v147
	v_cvt_pk_bf16_f32 v144, v186, v187
	v_cvt_pk_bf16_f32 v145, v188, v189
	v_cvt_pk_bf16_f32 v146, v190, v191
	v_cvt_pk_bf16_f32 v147, v192, v193
	global_store_dwordx4 v[210:211], v[144:147], off
	v_lshlrev_b32_e32 v178, 16, v148
	v_and_b32_e32 v148, 0xffff0000, v148
	v_lshlrev_b32_e32 v179, 16, v149
	v_and_b32_e32 v149, 0xffff0000, v149
	v_lshlrev_b32_e32 v180, 16, v150
	v_and_b32_e32 v150, 0xffff0000, v150
	v_lshlrev_b32_e32 v181, 16, v151
	v_and_b32_e32 v151, 0xffff0000, v151
	v_mul_f32_e32 v178, 0xbfb8aa3b, v178
	v_mul_f32_e32 v148, 0xbfb8aa3b, v148
	v_mul_f32_e32 v179, 0xbfb8aa3b, v179
	v_mul_f32_e32 v149, 0xbfb8aa3b, v149
	v_mul_f32_e32 v180, 0xbfb8aa3b, v180
	v_mul_f32_e32 v150, 0xbfb8aa3b, v150
	v_mul_f32_e32 v181, 0xbfb8aa3b, v181
	v_mul_f32_e32 v151, 0xbfb8aa3b, v151
	v_exp_f32_e32 v178, v178
	v_exp_f32_e32 v148, v148
	v_exp_f32_e32 v179, v179
	v_exp_f32_e32 v149, v149
	v_exp_f32_e32 v180, v180
	v_exp_f32_e32 v150, v150
	v_exp_f32_e32 v181, v181
	v_exp_f32_e32 v151, v151
	v_add_f32_e32 v178, 1.0, v178
	v_add_f32_e32 v148, 1.0, v148
	v_add_f32_e32 v179, 1.0, v179
	v_add_f32_e32 v149, 1.0, v149
	v_add_f32_e32 v180, 1.0, v180
	v_add_f32_e32 v150, 1.0, v150
	v_add_f32_e32 v181, 1.0, v181
	v_add_f32_e32 v151, 1.0, v151
	v_rcp_f32_e32 v178, v178
	v_rcp_f32_e32 v148, v148
	v_rcp_f32_e32 v179, v179
	v_rcp_f32_e32 v149, v149
	v_rcp_f32_e32 v180, v180
	v_rcp_f32_e32 v150, v150
	v_rcp_f32_e32 v181, v181
	v_rcp_f32_e32 v151, v151
	s_nop 0
	v_mul_f32_e32 v186, v28, v178
	v_mul_f32_e32 v187, v29, v148
	v_mul_f32_e32 v188, v30, v179
	v_mul_f32_e32 v189, v31, v149
	v_mul_f32_e32 v190, v24, v180
	v_mul_f32_e32 v191, v25, v150
	v_mul_f32_e32 v192, v26, v181
	v_mul_f32_e32 v193, v27, v151
	v_cvt_pk_bf16_f32 v148, v186, v187
	v_cvt_pk_bf16_f32 v149, v188, v189
	v_cvt_pk_bf16_f32 v150, v190, v191
	v_cvt_pk_bf16_f32 v151, v192, v193
	global_store_dwordx4 v[210:211], v[148:151], off offset:256
	s_mov_b64 s[98:99], 0x1e6000
	v_lshl_add_u64 v[210:211], v[216:217], 0, s[98:99]
	v_lshlrev_b32_e32 v178, 16, v152
	v_and_b32_e32 v152, 0xffff0000, v152
	v_lshlrev_b32_e32 v179, 16, v153
	v_and_b32_e32 v153, 0xffff0000, v153
	v_lshlrev_b32_e32 v180, 16, v154
	v_and_b32_e32 v154, 0xffff0000, v154
	v_lshlrev_b32_e32 v181, 16, v155
	v_and_b32_e32 v155, 0xffff0000, v155
	v_mul_f32_e32 v178, 0xbfb8aa3b, v178
	v_mul_f32_e32 v152, 0xbfb8aa3b, v152
	v_mul_f32_e32 v179, 0xbfb8aa3b, v179
	v_mul_f32_e32 v153, 0xbfb8aa3b, v153
	v_mul_f32_e32 v180, 0xbfb8aa3b, v180
	v_mul_f32_e32 v154, 0xbfb8aa3b, v154
	v_mul_f32_e32 v181, 0xbfb8aa3b, v181
	v_mul_f32_e32 v155, 0xbfb8aa3b, v155
	v_exp_f32_e32 v178, v178
	v_exp_f32_e32 v152, v152
	v_exp_f32_e32 v179, v179
	v_exp_f32_e32 v153, v153
	v_exp_f32_e32 v180, v180
	v_exp_f32_e32 v154, v154
	v_exp_f32_e32 v181, v181
	v_exp_f32_e32 v155, v155
	v_add_f32_e32 v178, 1.0, v178
	v_add_f32_e32 v152, 1.0, v152
	v_add_f32_e32 v179, 1.0, v179
	v_add_f32_e32 v153, 1.0, v153
	v_add_f32_e32 v180, 1.0, v180
	v_add_f32_e32 v154, 1.0, v154
	v_add_f32_e32 v181, 1.0, v181
	v_add_f32_e32 v155, 1.0, v155
	v_rcp_f32_e32 v178, v178
	v_rcp_f32_e32 v152, v152
	v_rcp_f32_e32 v179, v179
	v_rcp_f32_e32 v153, v153
	v_rcp_f32_e32 v180, v180
	v_rcp_f32_e32 v154, v154
	v_rcp_f32_e32 v181, v181
	v_rcp_f32_e32 v155, v155
	s_nop 0
	v_mul_f32_e32 v186, v52, v178
	v_mul_f32_e32 v187, v53, v152
	v_mul_f32_e32 v188, v54, v179
	v_mul_f32_e32 v189, v55, v153
	v_mul_f32_e32 v190, v48, v180
	v_mul_f32_e32 v191, v49, v154
	v_mul_f32_e32 v192, v50, v181
	v_mul_f32_e32 v193, v51, v155
	v_cvt_pk_bf16_f32 v152, v186, v187
	v_cvt_pk_bf16_f32 v153, v188, v189
	v_cvt_pk_bf16_f32 v154, v190, v191
	v_cvt_pk_bf16_f32 v155, v192, v193
	global_store_dwordx4 v[210:211], v[152:155], off
	v_lshlrev_b32_e32 v178, 16, v156
	v_and_b32_e32 v156, 0xffff0000, v156
	v_lshlrev_b32_e32 v179, 16, v157
	v_and_b32_e32 v157, 0xffff0000, v157
	v_lshlrev_b32_e32 v180, 16, v158
	v_and_b32_e32 v158, 0xffff0000, v158
	v_lshlrev_b32_e32 v181, 16, v159
	v_and_b32_e32 v159, 0xffff0000, v159
	v_mul_f32_e32 v178, 0xbfb8aa3b, v178
	v_mul_f32_e32 v156, 0xbfb8aa3b, v156
	v_mul_f32_e32 v179, 0xbfb8aa3b, v179
	v_mul_f32_e32 v157, 0xbfb8aa3b, v157
	v_mul_f32_e32 v180, 0xbfb8aa3b, v180
	v_mul_f32_e32 v158, 0xbfb8aa3b, v158
	v_mul_f32_e32 v181, 0xbfb8aa3b, v181
	v_mul_f32_e32 v159, 0xbfb8aa3b, v159
	v_exp_f32_e32 v178, v178
	v_exp_f32_e32 v156, v156
	v_exp_f32_e32 v179, v179
	v_exp_f32_e32 v157, v157
	v_exp_f32_e32 v180, v180
	v_exp_f32_e32 v158, v158
	v_exp_f32_e32 v181, v181
	v_exp_f32_e32 v159, v159
	v_add_f32_e32 v178, 1.0, v178
	v_add_f32_e32 v156, 1.0, v156
	v_add_f32_e32 v179, 1.0, v179
	v_add_f32_e32 v157, 1.0, v157
	v_add_f32_e32 v180, 1.0, v180
	v_add_f32_e32 v158, 1.0, v158
	v_add_f32_e32 v181, 1.0, v181
	v_add_f32_e32 v159, 1.0, v159
	v_rcp_f32_e32 v178, v178
	v_rcp_f32_e32 v156, v156
	v_rcp_f32_e32 v179, v179
	v_rcp_f32_e32 v157, v157
	v_rcp_f32_e32 v180, v180
	v_rcp_f32_e32 v158, v158
	v_rcp_f32_e32 v181, v181
	v_rcp_f32_e32 v159, v159
	s_nop 0
	v_mul_f32_e32 v186, v20, v178
	v_mul_f32_e32 v187, v21, v156
	v_mul_f32_e32 v188, v22, v179
	v_mul_f32_e32 v189, v23, v157
	v_mul_f32_e32 v190, v16, v180
	v_mul_f32_e32 v191, v17, v158
	v_mul_f32_e32 v192, v18, v181
	v_mul_f32_e32 v193, v19, v159
	v_cvt_pk_bf16_f32 v156, v186, v187
	v_cvt_pk_bf16_f32 v157, v188, v189
	v_cvt_pk_bf16_f32 v158, v190, v191
	v_cvt_pk_bf16_f32 v159, v192, v193
	global_store_dwordx4 v[210:211], v[156:159], off offset:256
	s_mov_b64 s[98:99], 0x21c000
	v_lshl_add_u64 v[210:211], v[216:217], 0, s[98:99]
	v_lshlrev_b32_e32 v178, 16, v160
	v_and_b32_e32 v160, 0xffff0000, v160
	v_lshlrev_b32_e32 v179, 16, v161
	v_and_b32_e32 v161, 0xffff0000, v161
	v_lshlrev_b32_e32 v180, 16, v162
	v_and_b32_e32 v162, 0xffff0000, v162
	v_lshlrev_b32_e32 v181, 16, v163
	v_and_b32_e32 v163, 0xffff0000, v163
	v_mul_f32_e32 v178, 0xbfb8aa3b, v178
	v_mul_f32_e32 v160, 0xbfb8aa3b, v160
	v_mul_f32_e32 v179, 0xbfb8aa3b, v179
	v_mul_f32_e32 v161, 0xbfb8aa3b, v161
	v_mul_f32_e32 v180, 0xbfb8aa3b, v180
	v_mul_f32_e32 v162, 0xbfb8aa3b, v162
	v_mul_f32_e32 v181, 0xbfb8aa3b, v181
	v_mul_f32_e32 v163, 0xbfb8aa3b, v163
	v_exp_f32_e32 v178, v178
	v_exp_f32_e32 v160, v160
	v_exp_f32_e32 v179, v179
	v_exp_f32_e32 v161, v161
	v_exp_f32_e32 v180, v180
	v_exp_f32_e32 v162, v162
	v_exp_f32_e32 v181, v181
	v_exp_f32_e32 v163, v163
	v_add_f32_e32 v178, 1.0, v178
	v_add_f32_e32 v160, 1.0, v160
	v_add_f32_e32 v179, 1.0, v179
	v_add_f32_e32 v161, 1.0, v161
	v_add_f32_e32 v180, 1.0, v180
	v_add_f32_e32 v162, 1.0, v162
	v_add_f32_e32 v181, 1.0, v181
	v_add_f32_e32 v163, 1.0, v163
	v_rcp_f32_e32 v178, v178
	v_rcp_f32_e32 v160, v160
	v_rcp_f32_e32 v179, v179
	v_rcp_f32_e32 v161, v161
	v_rcp_f32_e32 v180, v180
	v_rcp_f32_e32 v162, v162
	v_rcp_f32_e32 v181, v181
	v_rcp_f32_e32 v163, v163
	s_nop 0
	v_mul_f32_e32 v186, v44, v178
	v_mul_f32_e32 v187, v45, v160
	v_mul_f32_e32 v188, v46, v179
	v_mul_f32_e32 v189, v47, v161
	v_mul_f32_e32 v190, v40, v180
	v_mul_f32_e32 v191, v41, v162
	v_mul_f32_e32 v192, v42, v181
	v_mul_f32_e32 v193, v43, v163
	v_cvt_pk_bf16_f32 v160, v186, v187
	v_cvt_pk_bf16_f32 v161, v188, v189
	v_cvt_pk_bf16_f32 v162, v190, v191
	v_cvt_pk_bf16_f32 v163, v192, v193
	global_store_dwordx4 v[210:211], v[160:163], off
	v_lshlrev_b32_e32 v178, 16, v164
	v_and_b32_e32 v164, 0xffff0000, v164
	v_lshlrev_b32_e32 v179, 16, v165
	v_and_b32_e32 v165, 0xffff0000, v165
	v_lshlrev_b32_e32 v180, 16, v166
	v_and_b32_e32 v166, 0xffff0000, v166
	v_lshlrev_b32_e32 v181, 16, v167
	v_and_b32_e32 v167, 0xffff0000, v167
	v_mul_f32_e32 v178, 0xbfb8aa3b, v178
	v_mul_f32_e32 v164, 0xbfb8aa3b, v164
	v_mul_f32_e32 v179, 0xbfb8aa3b, v179
	v_mul_f32_e32 v165, 0xbfb8aa3b, v165
	v_mul_f32_e32 v180, 0xbfb8aa3b, v180
	v_mul_f32_e32 v166, 0xbfb8aa3b, v166
	v_mul_f32_e32 v181, 0xbfb8aa3b, v181
	v_mul_f32_e32 v167, 0xbfb8aa3b, v167
	v_exp_f32_e32 v178, v178
	v_exp_f32_e32 v164, v164
	v_exp_f32_e32 v179, v179
	v_exp_f32_e32 v165, v165
	v_exp_f32_e32 v180, v180
	v_exp_f32_e32 v166, v166
	v_exp_f32_e32 v181, v181
	v_exp_f32_e32 v167, v167
	v_add_f32_e32 v178, 1.0, v178
	v_add_f32_e32 v164, 1.0, v164
	v_add_f32_e32 v179, 1.0, v179
	v_add_f32_e32 v165, 1.0, v165
	v_add_f32_e32 v180, 1.0, v180
	v_add_f32_e32 v166, 1.0, v166
	v_add_f32_e32 v181, 1.0, v181
	v_add_f32_e32 v167, 1.0, v167
	v_rcp_f32_e32 v178, v178
	v_rcp_f32_e32 v164, v164
	v_rcp_f32_e32 v179, v179
	v_rcp_f32_e32 v165, v165
	v_rcp_f32_e32 v180, v180
	v_rcp_f32_e32 v166, v166
	v_rcp_f32_e32 v181, v181
	v_rcp_f32_e32 v167, v167
	s_nop 0
	v_mul_f32_e32 v186, v12, v178
	v_mul_f32_e32 v187, v13, v164
	v_mul_f32_e32 v188, v14, v179
	v_mul_f32_e32 v189, v15, v165
	v_mul_f32_e32 v190, v8, v180
	v_mul_f32_e32 v191, v9, v166
	v_mul_f32_e32 v192, v10, v181
	v_mul_f32_e32 v193, v11, v167
	v_cvt_pk_bf16_f32 v164, v186, v187
	v_cvt_pk_bf16_f32 v165, v188, v189
	v_cvt_pk_bf16_f32 v166, v190, v191
	v_cvt_pk_bf16_f32 v167, v192, v193
	global_store_dwordx4 v[210:211], v[164:167], off offset:256
	s_mov_b64 s[98:99], 0x252000
	v_lshl_add_u64 v[210:211], v[216:217], 0, s[98:99]
	v_lshlrev_b32_e32 v178, 16, v170
	v_and_b32_e32 v170, 0xffff0000, v170
	v_lshlrev_b32_e32 v179, 16, v171
	v_and_b32_e32 v171, 0xffff0000, v171
	v_lshlrev_b32_e32 v180, 16, v172
	v_and_b32_e32 v172, 0xffff0000, v172
	v_lshlrev_b32_e32 v181, 16, v173
	v_and_b32_e32 v173, 0xffff0000, v173
	v_mul_f32_e32 v178, 0xbfb8aa3b, v178
	v_mul_f32_e32 v170, 0xbfb8aa3b, v170
	v_mul_f32_e32 v179, 0xbfb8aa3b, v179
	v_mul_f32_e32 v171, 0xbfb8aa3b, v171
	v_mul_f32_e32 v180, 0xbfb8aa3b, v180
	v_mul_f32_e32 v172, 0xbfb8aa3b, v172
	v_mul_f32_e32 v181, 0xbfb8aa3b, v181
	v_mul_f32_e32 v173, 0xbfb8aa3b, v173
	v_exp_f32_e32 v178, v178
	v_exp_f32_e32 v170, v170
	v_exp_f32_e32 v179, v179
	v_exp_f32_e32 v171, v171
	v_exp_f32_e32 v180, v180
	v_exp_f32_e32 v172, v172
	v_exp_f32_e32 v181, v181
	v_exp_f32_e32 v173, v173
	v_add_f32_e32 v178, 1.0, v178
	v_add_f32_e32 v170, 1.0, v170
	v_add_f32_e32 v179, 1.0, v179
	v_add_f32_e32 v171, 1.0, v171
	v_add_f32_e32 v180, 1.0, v180
	v_add_f32_e32 v172, 1.0, v172
	v_add_f32_e32 v181, 1.0, v181
	v_add_f32_e32 v173, 1.0, v173
	v_rcp_f32_e32 v178, v178
	v_rcp_f32_e32 v170, v170
	v_rcp_f32_e32 v179, v179
	v_rcp_f32_e32 v171, v171
	v_rcp_f32_e32 v180, v180
	v_rcp_f32_e32 v172, v172
	v_rcp_f32_e32 v181, v181
	v_rcp_f32_e32 v173, v173
	s_nop 0
	v_mul_f32_e32 v186, v36, v178
	v_mul_f32_e32 v187, v37, v170
	v_mul_f32_e32 v188, v38, v179
	v_mul_f32_e32 v189, v39, v171
	v_mul_f32_e32 v190, v32, v180
	v_mul_f32_e32 v191, v33, v172
	v_mul_f32_e32 v192, v34, v181
	v_mul_f32_e32 v193, v35, v173
	v_cvt_pk_bf16_f32 v170, v186, v187
	v_cvt_pk_bf16_f32 v171, v188, v189
	v_cvt_pk_bf16_f32 v172, v190, v191
	v_cvt_pk_bf16_f32 v173, v192, v193
	global_store_dwordx4 v[210:211], v[170:173], off
	v_lshlrev_b32_e32 v178, 16, v174
	v_and_b32_e32 v174, 0xffff0000, v174
	v_lshlrev_b32_e32 v179, 16, v175
	v_and_b32_e32 v175, 0xffff0000, v175
	v_lshlrev_b32_e32 v180, 16, v176
	v_and_b32_e32 v176, 0xffff0000, v176
	v_lshlrev_b32_e32 v181, 16, v177
	v_and_b32_e32 v177, 0xffff0000, v177
	v_mul_f32_e32 v178, 0xbfb8aa3b, v178
	v_mul_f32_e32 v174, 0xbfb8aa3b, v174
	v_mul_f32_e32 v179, 0xbfb8aa3b, v179
	v_mul_f32_e32 v175, 0xbfb8aa3b, v175
	v_mul_f32_e32 v180, 0xbfb8aa3b, v180
	v_mul_f32_e32 v176, 0xbfb8aa3b, v176
	v_mul_f32_e32 v181, 0xbfb8aa3b, v181
	v_mul_f32_e32 v177, 0xbfb8aa3b, v177
	v_exp_f32_e32 v178, v178
	v_exp_f32_e32 v174, v174
	v_exp_f32_e32 v179, v179
	v_exp_f32_e32 v175, v175
	v_exp_f32_e32 v180, v180
	v_exp_f32_e32 v176, v176
	v_exp_f32_e32 v181, v181
	v_exp_f32_e32 v177, v177
	v_add_f32_e32 v178, 1.0, v178
	v_add_f32_e32 v174, 1.0, v174
	v_add_f32_e32 v179, 1.0, v179
	v_add_f32_e32 v175, 1.0, v175
	v_add_f32_e32 v180, 1.0, v180
	v_add_f32_e32 v176, 1.0, v176
	v_add_f32_e32 v181, 1.0, v181
	v_add_f32_e32 v177, 1.0, v177
	v_rcp_f32_e32 v178, v178
	v_rcp_f32_e32 v174, v174
	v_rcp_f32_e32 v179, v179
	v_rcp_f32_e32 v175, v175
	v_rcp_f32_e32 v180, v180
	v_rcp_f32_e32 v176, v176
	v_rcp_f32_e32 v181, v181
	v_rcp_f32_e32 v177, v177
	s_nop 0
	v_mul_f32_e32 v186, v4, v178
	v_mul_f32_e32 v187, v5, v174
	v_mul_f32_e32 v188, v6, v179
	v_mul_f32_e32 v189, v7, v175
	v_mul_f32_e32 v190, v0, v180
	v_mul_f32_e32 v191, v1, v176
	v_mul_f32_e32 v192, v2, v181
	v_mul_f32_e32 v193, v3, v177
	v_cvt_pk_bf16_f32 v174, v186, v187
	v_cvt_pk_bf16_f32 v175, v188, v189
	v_cvt_pk_bf16_f32 v176, v190, v191
	v_cvt_pk_bf16_f32 v177, v192, v193
	global_store_dwordx4 v[210:211], v[174:177], off offset:256
.Lmgepi_done:
	s_and_b64 vcc, exec, s[44:45]
	s_mov_b64 s[6:7], -1
	s_cbranch_vccnz .LBB0_1412
	s_branch .LBB0_1486
.LBB0_1486:
	s_and_b64 vcc, exec, s[46:47]
	s_cbranch_vccnz .LBB0_1488
	v_mov_b32_e32 v112, v113
	v_mov_b32_e32 v114, v113
	v_mov_b32_e32 v115, v113
	v_mov_b64_e32 v[0:1], v[112:113]
	v_mov_b64_e32 v[4:5], v[112:113]
	v_mov_b64_e32 v[8:9], v[112:113]
	v_mov_b64_e32 v[12:13], v[112:113]
	v_mov_b64_e32 v[16:17], v[112:113]
	v_mov_b64_e32 v[20:21], v[112:113]
	v_mov_b64_e32 v[24:25], v[112:113]
	v_mov_b64_e32 v[28:29], v[112:113]
	v_mov_b64_e32 v[32:33], v[112:113]
	v_mov_b64_e32 v[36:37], v[112:113]
	v_mov_b64_e32 v[40:41], v[112:113]
	v_mov_b64_e32 v[44:45], v[112:113]
	v_mov_b64_e32 v[48:49], v[112:113]
	v_mov_b64_e32 v[52:53], v[112:113]
	v_mov_b64_e32 v[56:57], v[112:113]
	v_mov_b64_e32 v[60:61], v[112:113]
	v_mov_b64_e32 v[64:65], v[112:113]
	v_mov_b64_e32 v[68:69], v[112:113]
	v_mov_b64_e32 v[72:73], v[112:113]
	v_mov_b64_e32 v[76:77], v[112:113]
	v_mov_b64_e32 v[80:81], v[112:113]
	v_mov_b64_e32 v[84:85], v[112:113]
	v_mov_b64_e32 v[88:89], v[112:113]
	v_mov_b64_e32 v[92:93], v[112:113]
	v_mov_b64_e32 v[96:97], v[112:113]
	v_mov_b64_e32 v[100:101], v[112:113]
	v_mov_b64_e32 v[104:105], v[112:113]
	v_mov_b64_e32 v[108:109], v[112:113]
	v_mov_b64_e32 v[118:119], v[114:115]
	v_mov_b64_e32 v[122:123], v[114:115]
	v_mov_b64_e32 v[126:127], v[114:115]
	v_mov_b64_e32 v[130:131], v[114:115]
	v_mov_b64_e32 v[2:3], v[114:115]
	v_mov_b64_e32 v[6:7], v[114:115]
	v_mov_b64_e32 v[10:11], v[114:115]
	v_mov_b64_e32 v[14:15], v[114:115]
	v_mov_b64_e32 v[18:19], v[114:115]
	v_mov_b64_e32 v[22:23], v[114:115]
	v_mov_b64_e32 v[26:27], v[114:115]
	v_mov_b64_e32 v[30:31], v[114:115]
	v_mov_b64_e32 v[34:35], v[114:115]
	v_mov_b64_e32 v[38:39], v[114:115]
	v_mov_b64_e32 v[42:43], v[114:115]
	v_mov_b64_e32 v[46:47], v[114:115]
	v_mov_b64_e32 v[50:51], v[114:115]
	v_mov_b64_e32 v[54:55], v[114:115]
	v_mov_b64_e32 v[58:59], v[114:115]
	v_mov_b64_e32 v[62:63], v[114:115]
	v_mov_b64_e32 v[66:67], v[114:115]
	v_mov_b64_e32 v[70:71], v[114:115]
	v_mov_b64_e32 v[74:75], v[114:115]
	v_mov_b64_e32 v[78:79], v[114:115]
	v_mov_b64_e32 v[82:83], v[114:115]
	v_mov_b64_e32 v[86:87], v[114:115]
	v_mov_b64_e32 v[90:91], v[114:115]
	v_mov_b64_e32 v[94:95], v[114:115]
	v_mov_b64_e32 v[98:99], v[114:115]
	v_mov_b64_e32 v[102:103], v[114:115]
	v_mov_b64_e32 v[106:107], v[114:115]
	v_mov_b64_e32 v[110:111], v[114:115]
	v_mov_b64_e32 v[116:117], v[112:113]
	v_mov_b64_e32 v[120:121], v[112:113]
	v_mov_b64_e32 v[124:125], v[112:113]
	v_mov_b64_e32 v[128:129], v[112:113]
